# FFN-up conv+gelu epilogue rewritten: fmac_dpp row shifts, packed gelu, 16-byte act stores
# speedup vs baseline: 1.0180x; 1.0105x over previous
; #define LAS __attribute__((address_space(3)))
;     __device__ __forceinline__ void operator()(Acc& acc, const Unit& u, int wr, int wc, int fr, int fq) const {
;     ...
;         asm volatile("s_waitcnt lgkmcnt(0)" ::: "memory"); __builtin_amdgcn_s_barrier(); asm volatile("" ::: "memory");
; #pragma unroll
;         for (int n = 0; n < 2; ++n) {
;             const int col = u.pn * HALF + cl + 4 * n;
;             const f32x4 w0a = *(const f32x4*)(cw + col), w1a = *(const f32x4*)(cw + FF2 + col), w2a = *(const f32x4*)(cw + 2 * FF2 + col), bba = *(const f32x4*)(cb + col);
;             const f32x4 w0b = *(const f32x4*)(cw + FF + col), w1b = *(const f32x4*)(cw + FF2 + FF + col), w2b = *(const f32x4*)(cw + 2 * FF2 + FF + col), bbb = *(const f32x4*)(cb + FF + col);
; #pragma unroll
;             for (int ai = 0; ai < 2; ++ai) {
;                 const int s = ai * 2 + wr;
;                 f32x4 ha = (f32x4){0.f, 0.f, 0.f, 0.f}, hb = ha;
;                 if (s > 0 && fr >= 14) { ha = *(const LAS f32x4*)(halo + (((s - 1) * 2 + (fr - 14)) * 2 + 0) * HALF + cl + 4 * n);
;                                           hb = *(const LAS f32x4*)(halo + (((s - 1) * 2 + (fr - 14)) * 2 + 1) * HALF + cl + 4 * n); }
; #pragma unroll
;                 for (int m = 0; m < 4; ++m) {
;                     const f32x4 ca = acc[ai][0][m][n], cbv = acc[ai][1][m][n];
;                     const f32x4 pa = (m > 0) ? acc[ai][0][m > 0 ? m - 1 : 0][n] : ha, pb = (m > 0) ? acc[ai][1][m > 0 ? m - 1 : 0][n] : hb;
;                     float res[4];
; #pragma unroll
;                     for (int e = 0; e < 4; ++e) {
;                         const float a1 = dpp_prev1(ca[e], pa[e]), a2 = dpp_prev2(ca[e], pa[e]);
;                         const float b1 = dpp_prev1(cbv[e], pb[e]), b2 = dpp_prev2(cbv[e], pb[e]);
;                         const float ua = bba[e] + w0a[e] * a2 + w1a[e] * a1 + w2a[e] * ca[e];
;                         const float ub = bbb[e] + w0b[e] * b2 + w1b[e] * b1 + w2b[e] * cbv[e];
;                         res[e] = gelu_tanh(ua) * ub; }
;                     const int row = row0 + ai * HALF + m * 16;
;                     u32x2 w; w.x = cvt_pk_bf16(res[0], res[1]); w.y = cvt_pk_bf16(res[2], res[3]);
;                     *(u32x2*)(act + (size_t)row * FF + col) = w;
.LBB0_937:
	s_or_b64 exec, exec, s[56:57]
	v_add_u32_e32 v172, v128, v170
	v_ashrrev_i32_e32 v173, 31, v172
	v_lshlrev_b64 v[140:141], 2, v[172:173]
	s_waitcnt lgkmcnt(0)
	s_barrier
	v_readlane_b32 s0, v254, 33
	v_readlane_b32 s1, v254, 34
	v_lshlrev_b64 v[168:169], 1, v[172:173]
	v_lshlrev_b32_e32 v162, 10, v226
	v_mov_b32_e32 v238, 0xbdd2d3e7
	v_mov_b32_e32 v239, 0xbdd2d3e7
	v_mov_b32_e32 v240, 0xc0135761
	v_mov_b32_e32 v241, 0xc0135761
	v_mov_b32_e32 v242, 1.0
	v_mov_b32_e32 v243, 1.0
	v_lshl_add_u64 v[246:247], s[0:1], 0, v[168:169]
	v_add3_u32 v244, s83, v162, v161
	v_mov_b32_e32 v245, v140
	global_load_dwordx4 v[144:147], v245, s[8:9]
	global_load_dwordx4 v[148:151], v245, s[30:31]
	global_load_dwordx4 v[152:155], v245, s[34:35]
	global_load_dwordx4 v[156:159], v245, s[10:11]
	global_load_dwordx4 v[128:131], v245, s[36:37]
	global_load_dwordx4 v[132:135], v245, s[38:39]
	global_load_dwordx4 v[136:139], v245, s[40:41]
	global_load_dwordx4 v[140:143], v245, s[44:45]
	v_mov_b32_e32 v160, 0
	v_mov_b32_e32 v161, 0
	v_mov_b32_e32 v162, 0
	v_mov_b32_e32 v163, 0
	v_mov_b32_e32 v164, 0
	v_mov_b32_e32 v165, 0
	v_mov_b32_e32 v166, 0
	v_mov_b32_e32 v167, 0
	s_and_b64 s[42:43], s[26:27], s[6:7]
	s_and_saveexec_b64 s[56:57], s[42:43]
	s_cbranch_execz .Lcv_h00
	v_add_u32_e32 v168, 0xffffc000, v244
	v_add_u32_e32 v169, 0xffffc200, v244
	ds_read_b128 v[160:163], v168
	ds_read_b128 v[164:167], v169
.Lcv_h00:
	s_or_b64 exec, exec, s[56:57]
	s_waitcnt vmcnt(0) lgkmcnt(0)
	v_pk_fma_f32 v[176:177], v[8:9], v[152:153], v[156:157]
	v_pk_fma_f32 v[178:179], v[10:11], v[154:155], v[158:159]
	v_pk_fma_f32 v[180:181], v[0:1], v[136:137], v[140:141]
	v_pk_fma_f32 v[182:183], v[2:3], v[138:139], v[142:143]
	v_fmac_f32_dpp v176, v8, v148 row_shr:1 row_mask:0xf bank_mask:0xf bound_ctrl:1
	v_fmac_f32_dpp v177, v9, v149 row_shr:1 row_mask:0xf bank_mask:0xf bound_ctrl:1
	v_fmac_f32_dpp v178, v10, v150 row_shr:1 row_mask:0xf bank_mask:0xf bound_ctrl:1
	v_fmac_f32_dpp v179, v11, v151 row_shr:1 row_mask:0xf bank_mask:0xf bound_ctrl:1
	v_fmac_f32_dpp v176, v8, v144 row_shr:2 row_mask:0xf bank_mask:0xf bound_ctrl:1
	v_fmac_f32_dpp v177, v9, v145 row_shr:2 row_mask:0xf bank_mask:0xf bound_ctrl:1
	v_fmac_f32_dpp v178, v10, v146 row_shr:2 row_mask:0xf bank_mask:0xf bound_ctrl:1
	v_fmac_f32_dpp v179, v11, v147 row_shr:2 row_mask:0xf bank_mask:0xf bound_ctrl:1
	v_fmac_f32_dpp v176, v160, v148 row_shl:15 row_mask:0xf bank_mask:0xf bound_ctrl:1
	v_fmac_f32_dpp v177, v161, v149 row_shl:15 row_mask:0xf bank_mask:0xf bound_ctrl:1
	v_fmac_f32_dpp v178, v162, v150 row_shl:15 row_mask:0xf bank_mask:0xf bound_ctrl:1
	v_fmac_f32_dpp v179, v163, v151 row_shl:15 row_mask:0xf bank_mask:0xf bound_ctrl:1
	v_fmac_f32_dpp v176, v160, v144 row_shl:14 row_mask:0xf bank_mask:0xf bound_ctrl:1
	v_fmac_f32_dpp v177, v161, v145 row_shl:14 row_mask:0xf bank_mask:0xf bound_ctrl:1
	v_fmac_f32_dpp v178, v162, v146 row_shl:14 row_mask:0xf bank_mask:0xf bound_ctrl:1
	v_fmac_f32_dpp v179, v163, v147 row_shl:14 row_mask:0xf bank_mask:0xf bound_ctrl:1
	v_fmac_f32_dpp v180, v0, v132 row_shr:1 row_mask:0xf bank_mask:0xf bound_ctrl:1
	v_fmac_f32_dpp v181, v1, v133 row_shr:1 row_mask:0xf bank_mask:0xf bound_ctrl:1
	v_fmac_f32_dpp v182, v2, v134 row_shr:1 row_mask:0xf bank_mask:0xf bound_ctrl:1
	v_fmac_f32_dpp v183, v3, v135 row_shr:1 row_mask:0xf bank_mask:0xf bound_ctrl:1
	v_fmac_f32_dpp v180, v0, v128 row_shr:2 row_mask:0xf bank_mask:0xf bound_ctrl:1
	v_fmac_f32_dpp v181, v1, v129 row_shr:2 row_mask:0xf bank_mask:0xf bound_ctrl:1
	v_fmac_f32_dpp v182, v2, v130 row_shr:2 row_mask:0xf bank_mask:0xf bound_ctrl:1
	v_fmac_f32_dpp v183, v3, v131 row_shr:2 row_mask:0xf bank_mask:0xf bound_ctrl:1
	v_fmac_f32_dpp v180, v164, v132 row_shl:15 row_mask:0xf bank_mask:0xf bound_ctrl:1
	v_fmac_f32_dpp v181, v165, v133 row_shl:15 row_mask:0xf bank_mask:0xf bound_ctrl:1
	v_fmac_f32_dpp v182, v166, v134 row_shl:15 row_mask:0xf bank_mask:0xf bound_ctrl:1
	v_fmac_f32_dpp v183, v167, v135 row_shl:15 row_mask:0xf bank_mask:0xf bound_ctrl:1
	v_fmac_f32_dpp v180, v164, v128 row_shl:14 row_mask:0xf bank_mask:0xf bound_ctrl:1
	v_fmac_f32_dpp v181, v165, v129 row_shl:14 row_mask:0xf bank_mask:0xf bound_ctrl:1
	v_fmac_f32_dpp v182, v166, v130 row_shl:14 row_mask:0xf bank_mask:0xf bound_ctrl:1
	v_fmac_f32_dpp v183, v167, v131 row_shl:14 row_mask:0xf bank_mask:0xf bound_ctrl:1
	v_pk_mul_f32 v[184:185], v[176:177], v[176:177]
	v_pk_mul_f32 v[186:187], v[178:179], v[178:179]
	v_pk_fma_f32 v[184:185], v[184:185], v[238:239], v[240:241]
	v_pk_fma_f32 v[186:187], v[186:187], v[238:239], v[240:241]
	v_pk_mul_f32 v[184:185], v[176:177], v[184:185]
	v_pk_mul_f32 v[186:187], v[178:179], v[186:187]
	v_exp_f32_e32 v184, v184
	v_exp_f32_e32 v185, v185
	v_exp_f32_e32 v186, v186
	v_exp_f32_e32 v187, v187
	s_nop 0
	v_pk_add_f32 v[184:185], v[184:185], v[242:243]
	v_pk_add_f32 v[186:187], v[186:187], v[242:243]
	v_rcp_f32_e32 v184, v184
	v_rcp_f32_e32 v185, v185
	v_rcp_f32_e32 v186, v186
	v_rcp_f32_e32 v187, v187
	s_nop 0
	v_pk_mul_f32 v[184:185], v[176:177], v[184:185]
	v_pk_mul_f32 v[186:187], v[178:179], v[186:187]
	v_pk_mul_f32 v[184:185], v[184:185], v[180:181]
	v_pk_mul_f32 v[186:187], v[186:187], v[182:183]
	v_cvt_pk_bf16_f32 v170, v184, v185
	v_cvt_pk_bf16_f32 v171, v186, v187
	v_pk_fma_f32 v[176:177], v[24:25], v[152:153], v[156:157]
	v_pk_fma_f32 v[178:179], v[26:27], v[154:155], v[158:159]
	v_pk_fma_f32 v[180:181], v[16:17], v[136:137], v[140:141]
	v_pk_fma_f32 v[182:183], v[18:19], v[138:139], v[142:143]
	v_fmac_f32_dpp v176, v24, v148 row_shr:1 row_mask:0xf bank_mask:0xf bound_ctrl:1
	v_fmac_f32_dpp v177, v25, v149 row_shr:1 row_mask:0xf bank_mask:0xf bound_ctrl:1
; __device__ __forceinline__ unsigned cvt_pk_bf16(float lo, float hi) { const f32x2 v = {lo, hi}; return __builtin_bit_cast(unsigned, __builtin_convertvector(v, bf16x2_t)); }
;     __device__ __forceinline__ void operator()(Acc& acc, const Unit& u, int wr, int wc, int fr, int fq) const {
;     ...
;                 for (int m = 0; m < 4; ++m) {
;                     const f32x4 ca = acc[ai][0][m][n], cbv = acc[ai][1][m][n];
;                     const f32x4 pa = (m > 0) ? acc[ai][0][m > 0 ? m - 1 : 0][n] : ha, pb = (m > 0) ? acc[ai][1][m > 0 ? m - 1 : 0][n] : hb;
;                     float res[4];
; #pragma unroll
;                     for (int e = 0; e < 4; ++e) {
;                         const float a1 = dpp_prev1(ca[e], pa[e]), a2 = dpp_prev2(ca[e], pa[e]);
;                         const float b1 = dpp_prev1(cbv[e], pb[e]), b2 = dpp_prev2(cbv[e], pb[e]);
;                         const float ua = bba[e] + w0a[e] * a2 + w1a[e] * a1 + w2a[e] * ca[e];
;                         const float ub = bbb[e] + w0b[e] * b2 + w1b[e] * b1 + w2b[e] * cbv[e];
;                         res[e] = gelu_tanh(ua) * ub; }
;                     const int row = row0 + ai * HALF + m * 16;
;                     u32x2 w; w.x = cvt_pk_bf16(res[0], res[1]); w.y = cvt_pk_bf16(res[2], res[3]);
;                     *(u32x2*)(act + (size_t)row * FF + col) = w;
	v_fmac_f32_dpp v178, v26, v150 row_shr:1 row_mask:0xf bank_mask:0xf bound_ctrl:1
	v_fmac_f32_dpp v179, v27, v151 row_shr:1 row_mask:0xf bank_mask:0xf bound_ctrl:1
	v_fmac_f32_dpp v176, v24, v144 row_shr:2 row_mask:0xf bank_mask:0xf bound_ctrl:1
	v_fmac_f32_dpp v177, v25, v145 row_shr:2 row_mask:0xf bank_mask:0xf bound_ctrl:1
	v_fmac_f32_dpp v178, v26, v146 row_shr:2 row_mask:0xf bank_mask:0xf bound_ctrl:1
	v_fmac_f32_dpp v179, v27, v147 row_shr:2 row_mask:0xf bank_mask:0xf bound_ctrl:1
	v_fmac_f32_dpp v176, v8, v148 row_shl:15 row_mask:0xf bank_mask:0xf bound_ctrl:1
	v_fmac_f32_dpp v177, v9, v149 row_shl:15 row_mask:0xf bank_mask:0xf bound_ctrl:1
	v_fmac_f32_dpp v178, v10, v150 row_shl:15 row_mask:0xf bank_mask:0xf bound_ctrl:1
	v_fmac_f32_dpp v179, v11, v151 row_shl:15 row_mask:0xf bank_mask:0xf bound_ctrl:1
	v_fmac_f32_dpp v176, v8, v144 row_shl:14 row_mask:0xf bank_mask:0xf bound_ctrl:1
	v_fmac_f32_dpp v177, v9, v145 row_shl:14 row_mask:0xf bank_mask:0xf bound_ctrl:1
	v_fmac_f32_dpp v178, v10, v146 row_shl:14 row_mask:0xf bank_mask:0xf bound_ctrl:1
	v_fmac_f32_dpp v179, v11, v147 row_shl:14 row_mask:0xf bank_mask:0xf bound_ctrl:1
	v_fmac_f32_dpp v180, v16, v132 row_shr:1 row_mask:0xf bank_mask:0xf bound_ctrl:1
	v_fmac_f32_dpp v181, v17, v133 row_shr:1 row_mask:0xf bank_mask:0xf bound_ctrl:1
	v_fmac_f32_dpp v182, v18, v134 row_shr:1 row_mask:0xf bank_mask:0xf bound_ctrl:1
	v_fmac_f32_dpp v183, v19, v135 row_shr:1 row_mask:0xf bank_mask:0xf bound_ctrl:1
	v_fmac_f32_dpp v180, v16, v128 row_shr:2 row_mask:0xf bank_mask:0xf bound_ctrl:1
	v_fmac_f32_dpp v181, v17, v129 row_shr:2 row_mask:0xf bank_mask:0xf bound_ctrl:1
	v_fmac_f32_dpp v182, v18, v130 row_shr:2 row_mask:0xf bank_mask:0xf bound_ctrl:1
	v_fmac_f32_dpp v183, v19, v131 row_shr:2 row_mask:0xf bank_mask:0xf bound_ctrl:1
	v_fmac_f32_dpp v180, v0, v132 row_shl:15 row_mask:0xf bank_mask:0xf bound_ctrl:1
	v_fmac_f32_dpp v181, v1, v133 row_shl:15 row_mask:0xf bank_mask:0xf bound_ctrl:1
	v_fmac_f32_dpp v182, v2, v134 row_shl:15 row_mask:0xf bank_mask:0xf bound_ctrl:1
	v_fmac_f32_dpp v183, v3, v135 row_shl:15 row_mask:0xf bank_mask:0xf bound_ctrl:1
	v_fmac_f32_dpp v180, v0, v128 row_shl:14 row_mask:0xf bank_mask:0xf bound_ctrl:1
	v_fmac_f32_dpp v181, v1, v129 row_shl:14 row_mask:0xf bank_mask:0xf bound_ctrl:1
	v_fmac_f32_dpp v182, v2, v130 row_shl:14 row_mask:0xf bank_mask:0xf bound_ctrl:1
	v_fmac_f32_dpp v183, v3, v131 row_shl:14 row_mask:0xf bank_mask:0xf bound_ctrl:1
	v_pk_mul_f32 v[184:185], v[176:177], v[176:177]
	v_pk_mul_f32 v[186:187], v[178:179], v[178:179]
	v_pk_fma_f32 v[184:185], v[184:185], v[238:239], v[240:241]
	v_pk_fma_f32 v[186:187], v[186:187], v[238:239], v[240:241]
	v_pk_mul_f32 v[184:185], v[176:177], v[184:185]
	v_pk_mul_f32 v[186:187], v[178:179], v[186:187]
	v_exp_f32_e32 v184, v184
	v_exp_f32_e32 v185, v185
	v_exp_f32_e32 v186, v186
	v_exp_f32_e32 v187, v187
	s_nop 0
	v_pk_add_f32 v[184:185], v[184:185], v[242:243]
	v_pk_add_f32 v[186:187], v[186:187], v[242:243]
	v_rcp_f32_e32 v184, v184
	v_rcp_f32_e32 v185, v185
	v_rcp_f32_e32 v186, v186
	v_rcp_f32_e32 v187, v187
	s_nop 0
	v_pk_mul_f32 v[184:185], v[176:177], v[184:185]
	v_pk_mul_f32 v[186:187], v[178:179], v[186:187]
	v_pk_mul_f32 v[184:185], v[184:185], v[180:181]
	v_pk_mul_f32 v[186:187], v[186:187], v[182:183]
	v_cvt_pk_bf16_f32 v172, v184, v185
	v_cvt_pk_bf16_f32 v173, v186, v187
	v_pk_fma_f32 v[176:177], v[40:41], v[152:153], v[156:157]
	v_pk_fma_f32 v[178:179], v[42:43], v[154:155], v[158:159]
	v_pk_fma_f32 v[180:181], v[32:33], v[136:137], v[140:141]
	v_pk_fma_f32 v[182:183], v[34:35], v[138:139], v[142:143]
	v_fmac_f32_dpp v176, v40, v148 row_shr:1 row_mask:0xf bank_mask:0xf bound_ctrl:1
	v_fmac_f32_dpp v177, v41, v149 row_shr:1 row_mask:0xf bank_mask:0xf bound_ctrl:1
	v_fmac_f32_dpp v178, v42, v150 row_shr:1 row_mask:0xf bank_mask:0xf bound_ctrl:1
	v_fmac_f32_dpp v179, v43, v151 row_shr:1 row_mask:0xf bank_mask:0xf bound_ctrl:1
	v_fmac_f32_dpp v176, v40, v144 row_shr:2 row_mask:0xf bank_mask:0xf bound_ctrl:1
	v_fmac_f32_dpp v177, v41, v145 row_shr:2 row_mask:0xf bank_mask:0xf bound_ctrl:1
	v_fmac_f32_dpp v178, v42, v146 row_shr:2 row_mask:0xf bank_mask:0xf bound_ctrl:1
	v_fmac_f32_dpp v179, v43, v147 row_shr:2 row_mask:0xf bank_mask:0xf bound_ctrl:1
	v_fmac_f32_dpp v176, v24, v148 row_shl:15 row_mask:0xf bank_mask:0xf bound_ctrl:1
	v_fmac_f32_dpp v177, v25, v149 row_shl:15 row_mask:0xf bank_mask:0xf bound_ctrl:1
	v_fmac_f32_dpp v178, v26, v150 row_shl:15 row_mask:0xf bank_mask:0xf bound_ctrl:1
	v_fmac_f32_dpp v179, v27, v151 row_shl:15 row_mask:0xf bank_mask:0xf bound_ctrl:1
	v_fmac_f32_dpp v176, v24, v144 row_shl:14 row_mask:0xf bank_mask:0xf bound_ctrl:1
	v_fmac_f32_dpp v177, v25, v145 row_shl:14 row_mask:0xf bank_mask:0xf bound_ctrl:1
	v_fmac_f32_dpp v178, v26, v146 row_shl:14 row_mask:0xf bank_mask:0xf bound_ctrl:1
	v_fmac_f32_dpp v179, v27, v147 row_shl:14 row_mask:0xf bank_mask:0xf bound_ctrl:1
	v_fmac_f32_dpp v180, v32, v132 row_shr:1 row_mask:0xf bank_mask:0xf bound_ctrl:1
	v_fmac_f32_dpp v181, v33, v133 row_shr:1 row_mask:0xf bank_mask:0xf bound_ctrl:1
	v_fmac_f32_dpp v182, v34, v134 row_shr:1 row_mask:0xf bank_mask:0xf bound_ctrl:1
	v_fmac_f32_dpp v183, v35, v135 row_shr:1 row_mask:0xf bank_mask:0xf bound_ctrl:1
	v_fmac_f32_dpp v180, v32, v128 row_shr:2 row_mask:0xf bank_mask:0xf bound_ctrl:1
	v_fmac_f32_dpp v181, v33, v129 row_shr:2 row_mask:0xf bank_mask:0xf bound_ctrl:1
	v_fmac_f32_dpp v182, v34, v130 row_shr:2 row_mask:0xf bank_mask:0xf bound_ctrl:1
	v_fmac_f32_dpp v183, v35, v131 row_shr:2 row_mask:0xf bank_mask:0xf bound_ctrl:1
	v_fmac_f32_dpp v180, v16, v132 row_shl:15 row_mask:0xf bank_mask:0xf bound_ctrl:1
; #define LAS __attribute__((address_space(3)))
; __device__ __forceinline__ unsigned cvt_pk_bf16(float lo, float hi) { const f32x2 v = {lo, hi}; return __builtin_bit_cast(unsigned, __builtin_convertvector(v, bf16x2_t)); }
;     __device__ __forceinline__ void operator()(Acc& acc, const Unit& u, int wr, int wc, int fr, int fq) const {
;     ...
;             for (int ai = 0; ai < 2; ++ai) {
;                 const int s = ai * 2 + wr;
;                 f32x4 ha = (f32x4){0.f, 0.f, 0.f, 0.f}, hb = ha;
;                 if (s > 0 && fr >= 14) { ha = *(const LAS f32x4*)(halo + (((s - 1) * 2 + (fr - 14)) * 2 + 0) * HALF + cl + 4 * n);
;                                           hb = *(const LAS f32x4*)(halo + (((s - 1) * 2 + (fr - 14)) * 2 + 1) * HALF + cl + 4 * n); }
; #pragma unroll
;                 for (int m = 0; m < 4; ++m) {
;                     const f32x4 ca = acc[ai][0][m][n], cbv = acc[ai][1][m][n];
;                     const f32x4 pa = (m > 0) ? acc[ai][0][m > 0 ? m - 1 : 0][n] : ha, pb = (m > 0) ? acc[ai][1][m > 0 ? m - 1 : 0][n] : hb;
;                     float res[4];
; #pragma unroll
;                     for (int e = 0; e < 4; ++e) {
;                         const float a1 = dpp_prev1(ca[e], pa[e]), a2 = dpp_prev2(ca[e], pa[e]);
;                         const float b1 = dpp_prev1(cbv[e], pb[e]), b2 = dpp_prev2(cbv[e], pb[e]);
;                         const float ua = bba[e] + w0a[e] * a2 + w1a[e] * a1 + w2a[e] * ca[e];
;                         const float ub = bbb[e] + w0b[e] * b2 + w1b[e] * b1 + w2b[e] * cbv[e];
;                         res[e] = gelu_tanh(ua) * ub; }
;                     const int row = row0 + ai * HALF + m * 16;
;                     u32x2 w; w.x = cvt_pk_bf16(res[0], res[1]); w.y = cvt_pk_bf16(res[2], res[3]);
;                     *(u32x2*)(act + (size_t)row * FF + col) = w;
	v_fmac_f32_dpp v181, v17, v133 row_shl:15 row_mask:0xf bank_mask:0xf bound_ctrl:1
	v_fmac_f32_dpp v182, v18, v134 row_shl:15 row_mask:0xf bank_mask:0xf bound_ctrl:1
	v_fmac_f32_dpp v183, v19, v135 row_shl:15 row_mask:0xf bank_mask:0xf bound_ctrl:1
	v_fmac_f32_dpp v180, v16, v128 row_shl:14 row_mask:0xf bank_mask:0xf bound_ctrl:1
	v_fmac_f32_dpp v181, v17, v129 row_shl:14 row_mask:0xf bank_mask:0xf bound_ctrl:1
	v_fmac_f32_dpp v182, v18, v130 row_shl:14 row_mask:0xf bank_mask:0xf bound_ctrl:1
	v_fmac_f32_dpp v183, v19, v131 row_shl:14 row_mask:0xf bank_mask:0xf bound_ctrl:1
	v_pk_mul_f32 v[184:185], v[176:177], v[176:177]
	v_pk_mul_f32 v[186:187], v[178:179], v[178:179]
	v_pk_fma_f32 v[184:185], v[184:185], v[238:239], v[240:241]
	v_pk_fma_f32 v[186:187], v[186:187], v[238:239], v[240:241]
	v_pk_mul_f32 v[184:185], v[176:177], v[184:185]
	v_pk_mul_f32 v[186:187], v[178:179], v[186:187]
	v_exp_f32_e32 v184, v184
	v_exp_f32_e32 v185, v185
	v_exp_f32_e32 v186, v186
	v_exp_f32_e32 v187, v187
	s_nop 0
	v_pk_add_f32 v[184:185], v[184:185], v[242:243]
	v_pk_add_f32 v[186:187], v[186:187], v[242:243]
	v_rcp_f32_e32 v184, v184
	v_rcp_f32_e32 v185, v185
	v_rcp_f32_e32 v186, v186
	v_rcp_f32_e32 v187, v187
	s_nop 0
	v_pk_mul_f32 v[184:185], v[176:177], v[184:185]
	v_pk_mul_f32 v[186:187], v[178:179], v[186:187]
	v_pk_mul_f32 v[184:185], v[184:185], v[180:181]
	v_pk_mul_f32 v[186:187], v[186:187], v[182:183]
	v_cvt_pk_bf16_f32 v174, v184, v185
	v_cvt_pk_bf16_f32 v175, v186, v187
	v_pk_fma_f32 v[176:177], v[56:57], v[152:153], v[156:157]
	v_pk_fma_f32 v[178:179], v[58:59], v[154:155], v[158:159]
	v_pk_fma_f32 v[180:181], v[48:49], v[136:137], v[140:141]
	v_pk_fma_f32 v[182:183], v[50:51], v[138:139], v[142:143]
	v_fmac_f32_dpp v176, v56, v148 row_shr:1 row_mask:0xf bank_mask:0xf bound_ctrl:1
	v_fmac_f32_dpp v177, v57, v149 row_shr:1 row_mask:0xf bank_mask:0xf bound_ctrl:1
	v_fmac_f32_dpp v178, v58, v150 row_shr:1 row_mask:0xf bank_mask:0xf bound_ctrl:1
	v_fmac_f32_dpp v179, v59, v151 row_shr:1 row_mask:0xf bank_mask:0xf bound_ctrl:1
	v_fmac_f32_dpp v176, v56, v144 row_shr:2 row_mask:0xf bank_mask:0xf bound_ctrl:1
	v_fmac_f32_dpp v177, v57, v145 row_shr:2 row_mask:0xf bank_mask:0xf bound_ctrl:1
	v_fmac_f32_dpp v178, v58, v146 row_shr:2 row_mask:0xf bank_mask:0xf bound_ctrl:1
	v_fmac_f32_dpp v179, v59, v147 row_shr:2 row_mask:0xf bank_mask:0xf bound_ctrl:1
	v_fmac_f32_dpp v176, v40, v148 row_shl:15 row_mask:0xf bank_mask:0xf bound_ctrl:1
	v_fmac_f32_dpp v177, v41, v149 row_shl:15 row_mask:0xf bank_mask:0xf bound_ctrl:1
	v_fmac_f32_dpp v178, v42, v150 row_shl:15 row_mask:0xf bank_mask:0xf bound_ctrl:1
	v_fmac_f32_dpp v179, v43, v151 row_shl:15 row_mask:0xf bank_mask:0xf bound_ctrl:1
	v_fmac_f32_dpp v176, v40, v144 row_shl:14 row_mask:0xf bank_mask:0xf bound_ctrl:1
	v_fmac_f32_dpp v177, v41, v145 row_shl:14 row_mask:0xf bank_mask:0xf bound_ctrl:1
	v_fmac_f32_dpp v178, v42, v146 row_shl:14 row_mask:0xf bank_mask:0xf bound_ctrl:1
	v_fmac_f32_dpp v179, v43, v147 row_shl:14 row_mask:0xf bank_mask:0xf bound_ctrl:1
	v_fmac_f32_dpp v180, v48, v132 row_shr:1 row_mask:0xf bank_mask:0xf bound_ctrl:1
	v_fmac_f32_dpp v181, v49, v133 row_shr:1 row_mask:0xf bank_mask:0xf bound_ctrl:1
	v_fmac_f32_dpp v182, v50, v134 row_shr:1 row_mask:0xf bank_mask:0xf bound_ctrl:1
	v_fmac_f32_dpp v183, v51, v135 row_shr:1 row_mask:0xf bank_mask:0xf bound_ctrl:1
	v_fmac_f32_dpp v180, v48, v128 row_shr:2 row_mask:0xf bank_mask:0xf bound_ctrl:1
	v_fmac_f32_dpp v181, v49, v129 row_shr:2 row_mask:0xf bank_mask:0xf bound_ctrl:1
	v_fmac_f32_dpp v182, v50, v130 row_shr:2 row_mask:0xf bank_mask:0xf bound_ctrl:1
	v_fmac_f32_dpp v183, v51, v131 row_shr:2 row_mask:0xf bank_mask:0xf bound_ctrl:1
	v_fmac_f32_dpp v180, v32, v132 row_shl:15 row_mask:0xf bank_mask:0xf bound_ctrl:1
	v_fmac_f32_dpp v181, v33, v133 row_shl:15 row_mask:0xf bank_mask:0xf bound_ctrl:1
	v_fmac_f32_dpp v182, v34, v134 row_shl:15 row_mask:0xf bank_mask:0xf bound_ctrl:1
	v_fmac_f32_dpp v183, v35, v135 row_shl:15 row_mask:0xf bank_mask:0xf bound_ctrl:1
	v_fmac_f32_dpp v180, v32, v128 row_shl:14 row_mask:0xf bank_mask:0xf bound_ctrl:1
	v_fmac_f32_dpp v181, v33, v129 row_shl:14 row_mask:0xf bank_mask:0xf bound_ctrl:1
	v_fmac_f32_dpp v182, v34, v130 row_shl:14 row_mask:0xf bank_mask:0xf bound_ctrl:1
	v_fmac_f32_dpp v183, v35, v131 row_shl:14 row_mask:0xf bank_mask:0xf bound_ctrl:1
	v_pk_mul_f32 v[184:185], v[176:177], v[176:177]
	v_pk_mul_f32 v[186:187], v[178:179], v[178:179]
	v_pk_fma_f32 v[184:185], v[184:185], v[238:239], v[240:241]
	v_pk_fma_f32 v[186:187], v[186:187], v[238:239], v[240:241]
	v_pk_mul_f32 v[184:185], v[176:177], v[184:185]
	v_pk_mul_f32 v[186:187], v[178:179], v[186:187]
	v_exp_f32_e32 v184, v184
	v_exp_f32_e32 v185, v185
	v_exp_f32_e32 v186, v186
	v_exp_f32_e32 v187, v187
	s_nop 0
	v_pk_add_f32 v[184:185], v[184:185], v[242:243]
	v_pk_add_f32 v[186:187], v[186:187], v[242:243]
	v_rcp_f32_e32 v184, v184
	v_rcp_f32_e32 v185, v185
	v_rcp_f32_e32 v186, v186
	v_rcp_f32_e32 v187, v187
	s_nop 0
	v_pk_mul_f32 v[184:185], v[176:177], v[184:185]
	v_pk_mul_f32 v[186:187], v[178:179], v[186:187]
	v_pk_mul_f32 v[184:185], v[184:185], v[180:181]
	v_pk_mul_f32 v[186:187], v[186:187], v[182:183]
	v_cvt_pk_bf16_f32 v237, v184, v185
	v_cvt_pk_bf16_f32 v248, v186, v187
	v_mov_b32_e32 v160, 0
	v_mov_b32_e32 v161, 0
	v_mov_b32_e32 v162, 0
	v_mov_b32_e32 v163, 0
	v_mov_b32_e32 v164, 0
	v_mov_b32_e32 v165, 0
	v_mov_b32_e32 v166, 0
	v_mov_b32_e32 v167, 0
	s_and_b64 s[42:43], s[28:29], s[6:7]
	s_and_saveexec_b64 s[56:57], s[42:43]
	s_cbranch_execz .Lcv_h01
	v_add_u32_e32 v168, 0xffffd000, v244
	v_add_u32_e32 v169, 0xffffd200, v244
	ds_read_b128 v[160:163], v168
	ds_read_b128 v[164:167], v169
; #define LAS __attribute__((address_space(3)))
; __device__ __forceinline__ unsigned cvt_pk_bf16(float lo, float hi) { const f32x2 v = {lo, hi}; return __builtin_bit_cast(unsigned, __builtin_convertvector(v, bf16x2_t)); }
;     __device__ __forceinline__ void operator()(Acc& acc, const Unit& u, int wr, int wc, int fr, int fq) const {
;     ...
;             for (int ai = 0; ai < 2; ++ai) {
;                 const int s = ai * 2 + wr;
;                 f32x4 ha = (f32x4){0.f, 0.f, 0.f, 0.f}, hb = ha;
;                 if (s > 0 && fr >= 14) { ha = *(const LAS f32x4*)(halo + (((s - 1) * 2 + (fr - 14)) * 2 + 0) * HALF + cl + 4 * n);
;                                           hb = *(const LAS f32x4*)(halo + (((s - 1) * 2 + (fr - 14)) * 2 + 1) * HALF + cl + 4 * n); }
; #pragma unroll
;                 for (int m = 0; m < 4; ++m) {
;                     const f32x4 ca = acc[ai][0][m][n], cbv = acc[ai][1][m][n];
;                     const f32x4 pa = (m > 0) ? acc[ai][0][m > 0 ? m - 1 : 0][n] : ha, pb = (m > 0) ? acc[ai][1][m > 0 ? m - 1 : 0][n] : hb;
;                     float res[4];
; #pragma unroll
;                     for (int e = 0; e < 4; ++e) {
;                         const float a1 = dpp_prev1(ca[e], pa[e]), a2 = dpp_prev2(ca[e], pa[e]);
;                         const float b1 = dpp_prev1(cbv[e], pb[e]), b2 = dpp_prev2(cbv[e], pb[e]);
;                         const float ua = bba[e] + w0a[e] * a2 + w1a[e] * a1 + w2a[e] * ca[e];
;                         const float ub = bbb[e] + w0b[e] * b2 + w1b[e] * b1 + w2b[e] * cbv[e];
;                         res[e] = gelu_tanh(ua) * ub; }
;                     const int row = row0 + ai * HALF + m * 16;
;                     u32x2 w; w.x = cvt_pk_bf16(res[0], res[1]); w.y = cvt_pk_bf16(res[2], res[3]);
;                     *(u32x2*)(act + (size_t)row * FF + col) = w;
.Lcv_h01:
	s_or_b64 exec, exec, s[56:57]
	s_waitcnt lgkmcnt(0)
	v_pk_fma_f32 v[176:177], v[64:65], v[152:153], v[156:157]
	v_pk_fma_f32 v[178:179], v[66:67], v[154:155], v[158:159]
	v_pk_fma_f32 v[180:181], v[72:73], v[136:137], v[140:141]
	v_pk_fma_f32 v[182:183], v[74:75], v[138:139], v[142:143]
	v_fmac_f32_dpp v176, v64, v148 row_shr:1 row_mask:0xf bank_mask:0xf bound_ctrl:1
	v_fmac_f32_dpp v177, v65, v149 row_shr:1 row_mask:0xf bank_mask:0xf bound_ctrl:1
	v_fmac_f32_dpp v178, v66, v150 row_shr:1 row_mask:0xf bank_mask:0xf bound_ctrl:1
	v_fmac_f32_dpp v179, v67, v151 row_shr:1 row_mask:0xf bank_mask:0xf bound_ctrl:1
	v_fmac_f32_dpp v176, v64, v144 row_shr:2 row_mask:0xf bank_mask:0xf bound_ctrl:1
	v_fmac_f32_dpp v177, v65, v145 row_shr:2 row_mask:0xf bank_mask:0xf bound_ctrl:1
	v_fmac_f32_dpp v178, v66, v146 row_shr:2 row_mask:0xf bank_mask:0xf bound_ctrl:1
	v_fmac_f32_dpp v179, v67, v147 row_shr:2 row_mask:0xf bank_mask:0xf bound_ctrl:1
	v_fmac_f32_dpp v176, v160, v148 row_shl:15 row_mask:0xf bank_mask:0xf bound_ctrl:1
	v_fmac_f32_dpp v177, v161, v149 row_shl:15 row_mask:0xf bank_mask:0xf bound_ctrl:1
	v_fmac_f32_dpp v178, v162, v150 row_shl:15 row_mask:0xf bank_mask:0xf bound_ctrl:1
	v_fmac_f32_dpp v179, v163, v151 row_shl:15 row_mask:0xf bank_mask:0xf bound_ctrl:1
	v_fmac_f32_dpp v176, v160, v144 row_shl:14 row_mask:0xf bank_mask:0xf bound_ctrl:1
	v_fmac_f32_dpp v177, v161, v145 row_shl:14 row_mask:0xf bank_mask:0xf bound_ctrl:1
	v_fmac_f32_dpp v178, v162, v146 row_shl:14 row_mask:0xf bank_mask:0xf bound_ctrl:1
	v_fmac_f32_dpp v179, v163, v147 row_shl:14 row_mask:0xf bank_mask:0xf bound_ctrl:1
	v_fmac_f32_dpp v180, v72, v132 row_shr:1 row_mask:0xf bank_mask:0xf bound_ctrl:1
	v_fmac_f32_dpp v181, v73, v133 row_shr:1 row_mask:0xf bank_mask:0xf bound_ctrl:1
	v_fmac_f32_dpp v182, v74, v134 row_shr:1 row_mask:0xf bank_mask:0xf bound_ctrl:1
	v_fmac_f32_dpp v183, v75, v135 row_shr:1 row_mask:0xf bank_mask:0xf bound_ctrl:1
	v_fmac_f32_dpp v180, v72, v128 row_shr:2 row_mask:0xf bank_mask:0xf bound_ctrl:1
	v_fmac_f32_dpp v181, v73, v129 row_shr:2 row_mask:0xf bank_mask:0xf bound_ctrl:1
	v_fmac_f32_dpp v182, v74, v130 row_shr:2 row_mask:0xf bank_mask:0xf bound_ctrl:1
	v_fmac_f32_dpp v183, v75, v131 row_shr:2 row_mask:0xf bank_mask:0xf bound_ctrl:1
	v_fmac_f32_dpp v180, v164, v132 row_shl:15 row_mask:0xf bank_mask:0xf bound_ctrl:1
	v_fmac_f32_dpp v181, v165, v133 row_shl:15 row_mask:0xf bank_mask:0xf bound_ctrl:1
	v_fmac_f32_dpp v182, v166, v134 row_shl:15 row_mask:0xf bank_mask:0xf bound_ctrl:1
	v_fmac_f32_dpp v183, v167, v135 row_shl:15 row_mask:0xf bank_mask:0xf bound_ctrl:1
	v_fmac_f32_dpp v180, v164, v128 row_shl:14 row_mask:0xf bank_mask:0xf bound_ctrl:1
	v_fmac_f32_dpp v181, v165, v129 row_shl:14 row_mask:0xf bank_mask:0xf bound_ctrl:1
	v_fmac_f32_dpp v182, v166, v130 row_shl:14 row_mask:0xf bank_mask:0xf bound_ctrl:1
	v_fmac_f32_dpp v183, v167, v131 row_shl:14 row_mask:0xf bank_mask:0xf bound_ctrl:1
	v_pk_mul_f32 v[184:185], v[176:177], v[176:177]
	v_pk_mul_f32 v[186:187], v[178:179], v[178:179]
	v_pk_fma_f32 v[184:185], v[184:185], v[238:239], v[240:241]
	v_pk_fma_f32 v[186:187], v[186:187], v[238:239], v[240:241]
	v_pk_mul_f32 v[184:185], v[176:177], v[184:185]
	v_pk_mul_f32 v[186:187], v[178:179], v[186:187]
	v_exp_f32_e32 v184, v184
	v_exp_f32_e32 v185, v185
	v_exp_f32_e32 v186, v186
	v_exp_f32_e32 v187, v187
	s_nop 0
	v_pk_add_f32 v[184:185], v[184:185], v[242:243]
	v_pk_add_f32 v[186:187], v[186:187], v[242:243]
	v_rcp_f32_e32 v184, v184
	v_rcp_f32_e32 v185, v185
	v_rcp_f32_e32 v186, v186
	v_rcp_f32_e32 v187, v187
	s_nop 0
	v_pk_mul_f32 v[184:185], v[176:177], v[184:185]
	v_pk_mul_f32 v[186:187], v[178:179], v[186:187]
	v_pk_mul_f32 v[184:185], v[184:185], v[180:181]
	v_pk_mul_f32 v[186:187], v[186:187], v[182:183]
	v_cvt_pk_bf16_f32 v249, v184, v185
	v_cvt_pk_bf16_f32 v250, v186, v187
	v_pk_fma_f32 v[176:177], v[80:81], v[152:153], v[156:157]
	v_pk_fma_f32 v[178:179], v[82:83], v[154:155], v[158:159]
	v_pk_fma_f32 v[180:181], v[88:89], v[136:137], v[140:141]
	v_pk_fma_f32 v[182:183], v[90:91], v[138:139], v[142:143]
	v_fmac_f32_dpp v176, v80, v148 row_shr:1 row_mask:0xf bank_mask:0xf bound_ctrl:1
	v_fmac_f32_dpp v177, v81, v149 row_shr:1 row_mask:0xf bank_mask:0xf bound_ctrl:1
	v_fmac_f32_dpp v178, v82, v150 row_shr:1 row_mask:0xf bank_mask:0xf bound_ctrl:1
	v_fmac_f32_dpp v179, v83, v151 row_shr:1 row_mask:0xf bank_mask:0xf bound_ctrl:1
	v_fmac_f32_dpp v176, v80, v144 row_shr:2 row_mask:0xf bank_mask:0xf bound_ctrl:1
	v_fmac_f32_dpp v177, v81, v145 row_shr:2 row_mask:0xf bank_mask:0xf bound_ctrl:1
	v_fmac_f32_dpp v178, v82, v146 row_shr:2 row_mask:0xf bank_mask:0xf bound_ctrl:1
	v_fmac_f32_dpp v179, v83, v147 row_shr:2 row_mask:0xf bank_mask:0xf bound_ctrl:1
	v_fmac_f32_dpp v176, v64, v148 row_shl:15 row_mask:0xf bank_mask:0xf bound_ctrl:1
	v_fmac_f32_dpp v177, v65, v149 row_shl:15 row_mask:0xf bank_mask:0xf bound_ctrl:1
	v_fmac_f32_dpp v178, v66, v150 row_shl:15 row_mask:0xf bank_mask:0xf bound_ctrl:1
	v_fmac_f32_dpp v179, v67, v151 row_shl:15 row_mask:0xf bank_mask:0xf bound_ctrl:1
	v_fmac_f32_dpp v176, v64, v144 row_shl:14 row_mask:0xf bank_mask:0xf bound_ctrl:1
	v_fmac_f32_dpp v177, v65, v145 row_shl:14 row_mask:0xf bank_mask:0xf bound_ctrl:1
	v_fmac_f32_dpp v178, v66, v146 row_shl:14 row_mask:0xf bank_mask:0xf bound_ctrl:1
	v_fmac_f32_dpp v179, v67, v147 row_shl:14 row_mask:0xf bank_mask:0xf bound_ctrl:1
	v_fmac_f32_dpp v180, v88, v132 row_shr:1 row_mask:0xf bank_mask:0xf bound_ctrl:1
	v_fmac_f32_dpp v181, v89, v133 row_shr:1 row_mask:0xf bank_mask:0xf bound_ctrl:1
	v_fmac_f32_dpp v182, v90, v134 row_shr:1 row_mask:0xf bank_mask:0xf bound_ctrl:1
; __device__ __forceinline__ unsigned cvt_pk_bf16(float lo, float hi) { const f32x2 v = {lo, hi}; return __builtin_bit_cast(unsigned, __builtin_convertvector(v, bf16x2_t)); }
;     __device__ __forceinline__ void operator()(Acc& acc, const Unit& u, int wr, int wc, int fr, int fq) const {
;     ...
;                 for (int m = 0; m < 4; ++m) {
;                     const f32x4 ca = acc[ai][0][m][n], cbv = acc[ai][1][m][n];
;                     const f32x4 pa = (m > 0) ? acc[ai][0][m > 0 ? m - 1 : 0][n] : ha, pb = (m > 0) ? acc[ai][1][m > 0 ? m - 1 : 0][n] : hb;
;                     float res[4];
; #pragma unroll
;                     for (int e = 0; e < 4; ++e) {
;                         const float a1 = dpp_prev1(ca[e], pa[e]), a2 = dpp_prev2(ca[e], pa[e]);
;                         const float b1 = dpp_prev1(cbv[e], pb[e]), b2 = dpp_prev2(cbv[e], pb[e]);
;                         const float ua = bba[e] + w0a[e] * a2 + w1a[e] * a1 + w2a[e] * ca[e];
;                         const float ub = bbb[e] + w0b[e] * b2 + w1b[e] * b1 + w2b[e] * cbv[e];
;                         res[e] = gelu_tanh(ua) * ub; }
;                     const int row = row0 + ai * HALF + m * 16;
;                     u32x2 w; w.x = cvt_pk_bf16(res[0], res[1]); w.y = cvt_pk_bf16(res[2], res[3]);
;                     *(u32x2*)(act + (size_t)row * FF + col) = w;
	v_fmac_f32_dpp v183, v91, v135 row_shr:1 row_mask:0xf bank_mask:0xf bound_ctrl:1
	v_fmac_f32_dpp v180, v88, v128 row_shr:2 row_mask:0xf bank_mask:0xf bound_ctrl:1
	v_fmac_f32_dpp v181, v89, v129 row_shr:2 row_mask:0xf bank_mask:0xf bound_ctrl:1
	v_fmac_f32_dpp v182, v90, v130 row_shr:2 row_mask:0xf bank_mask:0xf bound_ctrl:1
	v_fmac_f32_dpp v183, v91, v131 row_shr:2 row_mask:0xf bank_mask:0xf bound_ctrl:1
	v_fmac_f32_dpp v180, v72, v132 row_shl:15 row_mask:0xf bank_mask:0xf bound_ctrl:1
	v_fmac_f32_dpp v181, v73, v133 row_shl:15 row_mask:0xf bank_mask:0xf bound_ctrl:1
	v_fmac_f32_dpp v182, v74, v134 row_shl:15 row_mask:0xf bank_mask:0xf bound_ctrl:1
	v_fmac_f32_dpp v183, v75, v135 row_shl:15 row_mask:0xf bank_mask:0xf bound_ctrl:1
	v_fmac_f32_dpp v180, v72, v128 row_shl:14 row_mask:0xf bank_mask:0xf bound_ctrl:1
	v_fmac_f32_dpp v181, v73, v129 row_shl:14 row_mask:0xf bank_mask:0xf bound_ctrl:1
	v_fmac_f32_dpp v182, v74, v130 row_shl:14 row_mask:0xf bank_mask:0xf bound_ctrl:1
	v_fmac_f32_dpp v183, v75, v131 row_shl:14 row_mask:0xf bank_mask:0xf bound_ctrl:1
	v_pk_mul_f32 v[184:185], v[176:177], v[176:177]
	v_pk_mul_f32 v[186:187], v[178:179], v[178:179]
	v_pk_fma_f32 v[184:185], v[184:185], v[238:239], v[240:241]
	v_pk_fma_f32 v[186:187], v[186:187], v[238:239], v[240:241]
	v_pk_mul_f32 v[184:185], v[176:177], v[184:185]
	v_pk_mul_f32 v[186:187], v[178:179], v[186:187]
	v_exp_f32_e32 v184, v184
	v_exp_f32_e32 v185, v185
	v_exp_f32_e32 v186, v186
	v_exp_f32_e32 v187, v187
	s_nop 0
	v_pk_add_f32 v[184:185], v[184:185], v[242:243]
	v_pk_add_f32 v[186:187], v[186:187], v[242:243]
	v_rcp_f32_e32 v184, v184
	v_rcp_f32_e32 v185, v185
	v_rcp_f32_e32 v186, v186
	v_rcp_f32_e32 v187, v187
	s_nop 0
	v_pk_mul_f32 v[184:185], v[176:177], v[184:185]
	v_pk_mul_f32 v[186:187], v[178:179], v[186:187]
	v_pk_mul_f32 v[184:185], v[184:185], v[180:181]
	v_pk_mul_f32 v[186:187], v[186:187], v[182:183]
	v_cvt_pk_bf16_f32 v251, v184, v185
	v_cvt_pk_bf16_f32 v211, v186, v187
	v_pk_fma_f32 v[176:177], v[96:97], v[152:153], v[156:157]
	v_pk_fma_f32 v[178:179], v[98:99], v[154:155], v[158:159]
	v_pk_fma_f32 v[180:181], v[104:105], v[136:137], v[140:141]
	v_pk_fma_f32 v[182:183], v[106:107], v[138:139], v[142:143]
	v_fmac_f32_dpp v176, v96, v148 row_shr:1 row_mask:0xf bank_mask:0xf bound_ctrl:1
	v_fmac_f32_dpp v177, v97, v149 row_shr:1 row_mask:0xf bank_mask:0xf bound_ctrl:1
	v_fmac_f32_dpp v178, v98, v150 row_shr:1 row_mask:0xf bank_mask:0xf bound_ctrl:1
	v_fmac_f32_dpp v179, v99, v151 row_shr:1 row_mask:0xf bank_mask:0xf bound_ctrl:1
	v_fmac_f32_dpp v176, v96, v144 row_shr:2 row_mask:0xf bank_mask:0xf bound_ctrl:1
	v_fmac_f32_dpp v177, v97, v145 row_shr:2 row_mask:0xf bank_mask:0xf bound_ctrl:1
	v_fmac_f32_dpp v178, v98, v146 row_shr:2 row_mask:0xf bank_mask:0xf bound_ctrl:1
	v_fmac_f32_dpp v179, v99, v147 row_shr:2 row_mask:0xf bank_mask:0xf bound_ctrl:1
	v_fmac_f32_dpp v176, v80, v148 row_shl:15 row_mask:0xf bank_mask:0xf bound_ctrl:1
	v_fmac_f32_dpp v177, v81, v149 row_shl:15 row_mask:0xf bank_mask:0xf bound_ctrl:1
	v_fmac_f32_dpp v178, v82, v150 row_shl:15 row_mask:0xf bank_mask:0xf bound_ctrl:1
	v_fmac_f32_dpp v179, v83, v151 row_shl:15 row_mask:0xf bank_mask:0xf bound_ctrl:1
	v_fmac_f32_dpp v176, v80, v144 row_shl:14 row_mask:0xf bank_mask:0xf bound_ctrl:1
	v_fmac_f32_dpp v177, v81, v145 row_shl:14 row_mask:0xf bank_mask:0xf bound_ctrl:1
	v_fmac_f32_dpp v178, v82, v146 row_shl:14 row_mask:0xf bank_mask:0xf bound_ctrl:1
	v_fmac_f32_dpp v179, v83, v147 row_shl:14 row_mask:0xf bank_mask:0xf bound_ctrl:1
	v_fmac_f32_dpp v180, v104, v132 row_shr:1 row_mask:0xf bank_mask:0xf bound_ctrl:1
	v_fmac_f32_dpp v181, v105, v133 row_shr:1 row_mask:0xf bank_mask:0xf bound_ctrl:1
	v_fmac_f32_dpp v182, v106, v134 row_shr:1 row_mask:0xf bank_mask:0xf bound_ctrl:1
	v_fmac_f32_dpp v183, v107, v135 row_shr:1 row_mask:0xf bank_mask:0xf bound_ctrl:1
	v_fmac_f32_dpp v180, v104, v128 row_shr:2 row_mask:0xf bank_mask:0xf bound_ctrl:1
	v_fmac_f32_dpp v181, v105, v129 row_shr:2 row_mask:0xf bank_mask:0xf bound_ctrl:1
	v_fmac_f32_dpp v182, v106, v130 row_shr:2 row_mask:0xf bank_mask:0xf bound_ctrl:1
	v_fmac_f32_dpp v183, v107, v131 row_shr:2 row_mask:0xf bank_mask:0xf bound_ctrl:1
	v_fmac_f32_dpp v180, v88, v132 row_shl:15 row_mask:0xf bank_mask:0xf bound_ctrl:1
	v_fmac_f32_dpp v181, v89, v133 row_shl:15 row_mask:0xf bank_mask:0xf bound_ctrl:1
	v_fmac_f32_dpp v182, v90, v134 row_shl:15 row_mask:0xf bank_mask:0xf bound_ctrl:1
	v_fmac_f32_dpp v183, v91, v135 row_shl:15 row_mask:0xf bank_mask:0xf bound_ctrl:1
	v_fmac_f32_dpp v180, v88, v128 row_shl:14 row_mask:0xf bank_mask:0xf bound_ctrl:1
	v_fmac_f32_dpp v181, v89, v129 row_shl:14 row_mask:0xf bank_mask:0xf bound_ctrl:1
	v_fmac_f32_dpp v182, v90, v130 row_shl:14 row_mask:0xf bank_mask:0xf bound_ctrl:1
	v_fmac_f32_dpp v183, v91, v131 row_shl:14 row_mask:0xf bank_mask:0xf bound_ctrl:1
	v_pk_mul_f32 v[184:185], v[176:177], v[176:177]
	v_pk_mul_f32 v[186:187], v[178:179], v[178:179]
	v_pk_fma_f32 v[184:185], v[184:185], v[238:239], v[240:241]
	v_pk_fma_f32 v[186:187], v[186:187], v[238:239], v[240:241]
	v_pk_mul_f32 v[184:185], v[176:177], v[184:185]
	v_pk_mul_f32 v[186:187], v[178:179], v[186:187]
	v_exp_f32_e32 v184, v184
	v_exp_f32_e32 v185, v185
	v_exp_f32_e32 v186, v186
	v_exp_f32_e32 v187, v187
	s_nop 0
	v_pk_add_f32 v[184:185], v[184:185], v[242:243]
	v_pk_add_f32 v[186:187], v[186:187], v[242:243]
	v_rcp_f32_e32 v184, v184
	v_rcp_f32_e32 v185, v185
	v_rcp_f32_e32 v186, v186
	v_rcp_f32_e32 v187, v187
	s_nop 0
	v_pk_mul_f32 v[184:185], v[176:177], v[184:185]
	v_pk_mul_f32 v[186:187], v[178:179], v[186:187]
	v_pk_mul_f32 v[184:185], v[184:185], v[180:181]
; #define LAS __attribute__((address_space(3)))
; __device__ __forceinline__ unsigned cvt_pk_bf16(float lo, float hi) { const f32x2 v = {lo, hi}; return __builtin_bit_cast(unsigned, __builtin_convertvector(v, bf16x2_t)); }
;     __device__ __forceinline__ void operator()(Acc& acc, const Unit& u, int wr, int wc, int fr, int fq) const {
;     ...
; #pragma unroll
;         for (int n = 0; n < 2; ++n) {
;             const int col = u.pn * HALF + cl + 4 * n;
;             const f32x4 w0a = *(const f32x4*)(cw + col), w1a = *(const f32x4*)(cw + FF2 + col), w2a = *(const f32x4*)(cw + 2 * FF2 + col), bba = *(const f32x4*)(cb + col);
;             const f32x4 w0b = *(const f32x4*)(cw + FF + col), w1b = *(const f32x4*)(cw + FF2 + FF + col), w2b = *(const f32x4*)(cw + 2 * FF2 + FF + col), bbb = *(const f32x4*)(cb + FF + col);
; #pragma unroll
;             for (int ai = 0; ai < 2; ++ai) {
;                 const int s = ai * 2 + wr;
;                 f32x4 ha = (f32x4){0.f, 0.f, 0.f, 0.f}, hb = ha;
;                 if (s > 0 && fr >= 14) { ha = *(const LAS f32x4*)(halo + (((s - 1) * 2 + (fr - 14)) * 2 + 0) * HALF + cl + 4 * n);
;                                           hb = *(const LAS f32x4*)(halo + (((s - 1) * 2 + (fr - 14)) * 2 + 1) * HALF + cl + 4 * n); }
; #pragma unroll
;                 for (int m = 0; m < 4; ++m) {
;                     const f32x4 ca = acc[ai][0][m][n], cbv = acc[ai][1][m][n];
;                     const f32x4 pa = (m > 0) ? acc[ai][0][m > 0 ? m - 1 : 0][n] : ha, pb = (m > 0) ? acc[ai][1][m > 0 ? m - 1 : 0][n] : hb;
;                     float res[4];
; #pragma unroll
;                     for (int e = 0; e < 4; ++e) {
;                         const float a1 = dpp_prev1(ca[e], pa[e]), a2 = dpp_prev2(ca[e], pa[e]);
;                         const float b1 = dpp_prev1(cbv[e], pb[e]), b2 = dpp_prev2(cbv[e], pb[e]);
;                         const float ua = bba[e] + w0a[e] * a2 + w1a[e] * a1 + w2a[e] * ca[e];
;                         const float ub = bbb[e] + w0b[e] * b2 + w1b[e] * b1 + w2b[e] * cbv[e];
;                         res[e] = gelu_tanh(ua) * ub; }
;                     const int row = row0 + ai * HALF + m * 16;
;                     u32x2 w; w.x = cvt_pk_bf16(res[0], res[1]); w.y = cvt_pk_bf16(res[2], res[3]);
;                     *(u32x2*)(act + (size_t)row * FF + col) = w;
	v_pk_mul_f32 v[186:187], v[186:187], v[182:183]
	v_cvt_pk_bf16_f32 v213, v184, v185
	v_cvt_pk_bf16_f32 v215, v186, v187
	v_pk_fma_f32 v[176:177], v[112:113], v[152:153], v[156:157]
	v_pk_fma_f32 v[178:179], v[114:115], v[154:155], v[158:159]
	v_pk_fma_f32 v[180:181], v[120:121], v[136:137], v[140:141]
	v_pk_fma_f32 v[182:183], v[122:123], v[138:139], v[142:143]
	v_fmac_f32_dpp v176, v112, v148 row_shr:1 row_mask:0xf bank_mask:0xf bound_ctrl:1
	v_fmac_f32_dpp v177, v113, v149 row_shr:1 row_mask:0xf bank_mask:0xf bound_ctrl:1
	v_fmac_f32_dpp v178, v114, v150 row_shr:1 row_mask:0xf bank_mask:0xf bound_ctrl:1
	v_fmac_f32_dpp v179, v115, v151 row_shr:1 row_mask:0xf bank_mask:0xf bound_ctrl:1
	v_fmac_f32_dpp v176, v112, v144 row_shr:2 row_mask:0xf bank_mask:0xf bound_ctrl:1
	v_fmac_f32_dpp v177, v113, v145 row_shr:2 row_mask:0xf bank_mask:0xf bound_ctrl:1
	v_fmac_f32_dpp v178, v114, v146 row_shr:2 row_mask:0xf bank_mask:0xf bound_ctrl:1
	v_fmac_f32_dpp v179, v115, v147 row_shr:2 row_mask:0xf bank_mask:0xf bound_ctrl:1
	v_fmac_f32_dpp v176, v96, v148 row_shl:15 row_mask:0xf bank_mask:0xf bound_ctrl:1
	v_fmac_f32_dpp v177, v97, v149 row_shl:15 row_mask:0xf bank_mask:0xf bound_ctrl:1
	v_fmac_f32_dpp v178, v98, v150 row_shl:15 row_mask:0xf bank_mask:0xf bound_ctrl:1
	v_fmac_f32_dpp v179, v99, v151 row_shl:15 row_mask:0xf bank_mask:0xf bound_ctrl:1
	v_fmac_f32_dpp v176, v96, v144 row_shl:14 row_mask:0xf bank_mask:0xf bound_ctrl:1
	v_fmac_f32_dpp v177, v97, v145 row_shl:14 row_mask:0xf bank_mask:0xf bound_ctrl:1
	v_fmac_f32_dpp v178, v98, v146 row_shl:14 row_mask:0xf bank_mask:0xf bound_ctrl:1
	v_fmac_f32_dpp v179, v99, v147 row_shl:14 row_mask:0xf bank_mask:0xf bound_ctrl:1
	v_fmac_f32_dpp v180, v120, v132 row_shr:1 row_mask:0xf bank_mask:0xf bound_ctrl:1
	v_fmac_f32_dpp v181, v121, v133 row_shr:1 row_mask:0xf bank_mask:0xf bound_ctrl:1
	v_fmac_f32_dpp v182, v122, v134 row_shr:1 row_mask:0xf bank_mask:0xf bound_ctrl:1
	v_fmac_f32_dpp v183, v123, v135 row_shr:1 row_mask:0xf bank_mask:0xf bound_ctrl:1
	v_fmac_f32_dpp v180, v120, v128 row_shr:2 row_mask:0xf bank_mask:0xf bound_ctrl:1
	v_fmac_f32_dpp v181, v121, v129 row_shr:2 row_mask:0xf bank_mask:0xf bound_ctrl:1
	v_fmac_f32_dpp v182, v122, v130 row_shr:2 row_mask:0xf bank_mask:0xf bound_ctrl:1
	v_fmac_f32_dpp v183, v123, v131 row_shr:2 row_mask:0xf bank_mask:0xf bound_ctrl:1
	v_fmac_f32_dpp v180, v104, v132 row_shl:15 row_mask:0xf bank_mask:0xf bound_ctrl:1
	v_fmac_f32_dpp v181, v105, v133 row_shl:15 row_mask:0xf bank_mask:0xf bound_ctrl:1
	v_fmac_f32_dpp v182, v106, v134 row_shl:15 row_mask:0xf bank_mask:0xf bound_ctrl:1
	v_fmac_f32_dpp v183, v107, v135 row_shl:15 row_mask:0xf bank_mask:0xf bound_ctrl:1
	v_fmac_f32_dpp v180, v104, v128 row_shl:14 row_mask:0xf bank_mask:0xf bound_ctrl:1
	v_fmac_f32_dpp v181, v105, v129 row_shl:14 row_mask:0xf bank_mask:0xf bound_ctrl:1
	v_fmac_f32_dpp v182, v106, v130 row_shl:14 row_mask:0xf bank_mask:0xf bound_ctrl:1
	v_fmac_f32_dpp v183, v107, v131 row_shl:14 row_mask:0xf bank_mask:0xf bound_ctrl:1
	v_pk_mul_f32 v[184:185], v[176:177], v[176:177]
	v_pk_mul_f32 v[186:187], v[178:179], v[178:179]
	v_pk_fma_f32 v[184:185], v[184:185], v[238:239], v[240:241]
	v_pk_fma_f32 v[186:187], v[186:187], v[238:239], v[240:241]
	v_pk_mul_f32 v[184:185], v[176:177], v[184:185]
	v_pk_mul_f32 v[186:187], v[178:179], v[186:187]
	v_exp_f32_e32 v184, v184
	v_exp_f32_e32 v185, v185
	v_exp_f32_e32 v186, v186
	v_exp_f32_e32 v187, v187
	s_nop 0
	v_pk_add_f32 v[184:185], v[184:185], v[242:243]
	v_pk_add_f32 v[186:187], v[186:187], v[242:243]
	v_rcp_f32_e32 v184, v184
	v_rcp_f32_e32 v185, v185
	v_rcp_f32_e32 v186, v186
	v_rcp_f32_e32 v187, v187
	s_nop 0
	v_pk_mul_f32 v[184:185], v[176:177], v[184:185]
	v_pk_mul_f32 v[186:187], v[178:179], v[186:187]
	v_pk_mul_f32 v[184:185], v[184:185], v[180:181]
	v_pk_mul_f32 v[186:187], v[186:187], v[182:183]
	v_cvt_pk_bf16_f32 v217, v184, v185
	v_cvt_pk_bf16_f32 v219, v186, v187
	global_load_dwordx4 v[144:147], v245, s[8:9] offset:16
	global_load_dwordx4 v[148:151], v245, s[30:31] offset:16
	global_load_dwordx4 v[152:155], v245, s[34:35] offset:16
	global_load_dwordx4 v[156:159], v245, s[10:11] offset:16
	global_load_dwordx4 v[128:131], v245, s[36:37] offset:16
	global_load_dwordx4 v[132:135], v245, s[38:39] offset:16
	global_load_dwordx4 v[136:139], v245, s[40:41] offset:16
	global_load_dwordx4 v[140:143], v245, s[44:45] offset:16
	v_mov_b32_e32 v160, 0
	v_mov_b32_e32 v161, 0
	v_mov_b32_e32 v162, 0
	v_mov_b32_e32 v163, 0
	v_mov_b32_e32 v164, 0
	v_mov_b32_e32 v165, 0
	v_mov_b32_e32 v166, 0
	v_mov_b32_e32 v167, 0
	s_and_b64 s[42:43], s[26:27], s[6:7]
	s_and_saveexec_b64 s[56:57], s[42:43]
	s_cbranch_execz .Lcv_h10
	v_add_u32_e32 v168, 0xffffc010, v244
	v_add_u32_e32 v169, 0xffffc210, v244
	ds_read_b128 v[160:163], v168
	ds_read_b128 v[164:167], v169
; #define LAS __attribute__((address_space(3)))
; __device__ __forceinline__ unsigned cvt_pk_bf16(float lo, float hi) { const f32x2 v = {lo, hi}; return __builtin_bit_cast(unsigned, __builtin_convertvector(v, bf16x2_t)); }
;     __device__ __forceinline__ void operator()(Acc& acc, const Unit& u, int wr, int wc, int fr, int fq) const {
;     ...
;         for (int n = 0; n < 2; ++n) {
;             const int col = u.pn * HALF + cl + 4 * n;
;             const f32x4 w0a = *(const f32x4*)(cw + col), w1a = *(const f32x4*)(cw + FF2 + col), w2a = *(const f32x4*)(cw + 2 * FF2 + col), bba = *(const f32x4*)(cb + col);
;             const f32x4 w0b = *(const f32x4*)(cw + FF + col), w1b = *(const f32x4*)(cw + FF2 + FF + col), w2b = *(const f32x4*)(cw + 2 * FF2 + FF + col), bbb = *(const f32x4*)(cb + FF + col);
; #pragma unroll
;             for (int ai = 0; ai < 2; ++ai) {
;                 const int s = ai * 2 + wr;
;                 f32x4 ha = (f32x4){0.f, 0.f, 0.f, 0.f}, hb = ha;
;                 if (s > 0 && fr >= 14) { ha = *(const LAS f32x4*)(halo + (((s - 1) * 2 + (fr - 14)) * 2 + 0) * HALF + cl + 4 * n);
;                                           hb = *(const LAS f32x4*)(halo + (((s - 1) * 2 + (fr - 14)) * 2 + 1) * HALF + cl + 4 * n); }
; #pragma unroll
;                 for (int m = 0; m < 4; ++m) {
;                     const f32x4 ca = acc[ai][0][m][n], cbv = acc[ai][1][m][n];
;                     const f32x4 pa = (m > 0) ? acc[ai][0][m > 0 ? m - 1 : 0][n] : ha, pb = (m > 0) ? acc[ai][1][m > 0 ? m - 1 : 0][n] : hb;
;                     float res[4];
; #pragma unroll
;                     for (int e = 0; e < 4; ++e) {
;                         const float a1 = dpp_prev1(ca[e], pa[e]), a2 = dpp_prev2(ca[e], pa[e]);
;                         const float b1 = dpp_prev1(cbv[e], pb[e]), b2 = dpp_prev2(cbv[e], pb[e]);
;                         const float ua = bba[e] + w0a[e] * a2 + w1a[e] * a1 + w2a[e] * ca[e];
;                         const float ub = bbb[e] + w0b[e] * b2 + w1b[e] * b1 + w2b[e] * cbv[e];
;                         res[e] = gelu_tanh(ua) * ub; }
;                     const int row = row0 + ai * HALF + m * 16;
;                     u32x2 w; w.x = cvt_pk_bf16(res[0], res[1]); w.y = cvt_pk_bf16(res[2], res[3]);
;                     *(u32x2*)(act + (size_t)row * FF + col) = w;
;                     asm volatile("" ::: "memory"); } } }
.Lcv_h10:
	s_or_b64 exec, exec, s[56:57]
	s_waitcnt vmcnt(0) lgkmcnt(0)
	v_pk_fma_f32 v[176:177], v[12:13], v[152:153], v[156:157]
	v_pk_fma_f32 v[178:179], v[14:15], v[154:155], v[158:159]
	v_pk_fma_f32 v[180:181], v[4:5], v[136:137], v[140:141]
	v_pk_fma_f32 v[182:183], v[6:7], v[138:139], v[142:143]
	v_fmac_f32_dpp v176, v12, v148 row_shr:1 row_mask:0xf bank_mask:0xf bound_ctrl:1
	v_fmac_f32_dpp v177, v13, v149 row_shr:1 row_mask:0xf bank_mask:0xf bound_ctrl:1
	v_fmac_f32_dpp v178, v14, v150 row_shr:1 row_mask:0xf bank_mask:0xf bound_ctrl:1
	v_fmac_f32_dpp v179, v15, v151 row_shr:1 row_mask:0xf bank_mask:0xf bound_ctrl:1
	v_fmac_f32_dpp v176, v12, v144 row_shr:2 row_mask:0xf bank_mask:0xf bound_ctrl:1
	v_fmac_f32_dpp v177, v13, v145 row_shr:2 row_mask:0xf bank_mask:0xf bound_ctrl:1
	v_fmac_f32_dpp v178, v14, v146 row_shr:2 row_mask:0xf bank_mask:0xf bound_ctrl:1
	v_fmac_f32_dpp v179, v15, v147 row_shr:2 row_mask:0xf bank_mask:0xf bound_ctrl:1
	v_fmac_f32_dpp v176, v160, v148 row_shl:15 row_mask:0xf bank_mask:0xf bound_ctrl:1
	v_fmac_f32_dpp v177, v161, v149 row_shl:15 row_mask:0xf bank_mask:0xf bound_ctrl:1
	v_fmac_f32_dpp v178, v162, v150 row_shl:15 row_mask:0xf bank_mask:0xf bound_ctrl:1
	v_fmac_f32_dpp v179, v163, v151 row_shl:15 row_mask:0xf bank_mask:0xf bound_ctrl:1
	v_fmac_f32_dpp v176, v160, v144 row_shl:14 row_mask:0xf bank_mask:0xf bound_ctrl:1
	v_fmac_f32_dpp v177, v161, v145 row_shl:14 row_mask:0xf bank_mask:0xf bound_ctrl:1
	v_fmac_f32_dpp v178, v162, v146 row_shl:14 row_mask:0xf bank_mask:0xf bound_ctrl:1
	v_fmac_f32_dpp v179, v163, v147 row_shl:14 row_mask:0xf bank_mask:0xf bound_ctrl:1
	v_fmac_f32_dpp v180, v4, v132 row_shr:1 row_mask:0xf bank_mask:0xf bound_ctrl:1
	v_fmac_f32_dpp v181, v5, v133 row_shr:1 row_mask:0xf bank_mask:0xf bound_ctrl:1
	v_fmac_f32_dpp v182, v6, v134 row_shr:1 row_mask:0xf bank_mask:0xf bound_ctrl:1
	v_fmac_f32_dpp v183, v7, v135 row_shr:1 row_mask:0xf bank_mask:0xf bound_ctrl:1
	v_fmac_f32_dpp v180, v4, v128 row_shr:2 row_mask:0xf bank_mask:0xf bound_ctrl:1
	v_fmac_f32_dpp v181, v5, v129 row_shr:2 row_mask:0xf bank_mask:0xf bound_ctrl:1
	v_fmac_f32_dpp v182, v6, v130 row_shr:2 row_mask:0xf bank_mask:0xf bound_ctrl:1
	v_fmac_f32_dpp v183, v7, v131 row_shr:2 row_mask:0xf bank_mask:0xf bound_ctrl:1
	v_fmac_f32_dpp v180, v164, v132 row_shl:15 row_mask:0xf bank_mask:0xf bound_ctrl:1
	v_fmac_f32_dpp v181, v165, v133 row_shl:15 row_mask:0xf bank_mask:0xf bound_ctrl:1
	v_fmac_f32_dpp v182, v166, v134 row_shl:15 row_mask:0xf bank_mask:0xf bound_ctrl:1
	v_fmac_f32_dpp v183, v167, v135 row_shl:15 row_mask:0xf bank_mask:0xf bound_ctrl:1
	v_fmac_f32_dpp v180, v164, v128 row_shl:14 row_mask:0xf bank_mask:0xf bound_ctrl:1
	v_fmac_f32_dpp v181, v165, v129 row_shl:14 row_mask:0xf bank_mask:0xf bound_ctrl:1
	v_fmac_f32_dpp v182, v166, v130 row_shl:14 row_mask:0xf bank_mask:0xf bound_ctrl:1
	v_fmac_f32_dpp v183, v167, v131 row_shl:14 row_mask:0xf bank_mask:0xf bound_ctrl:1
	v_pk_mul_f32 v[184:185], v[176:177], v[176:177]
	v_pk_mul_f32 v[186:187], v[178:179], v[178:179]
	v_pk_fma_f32 v[184:185], v[184:185], v[238:239], v[240:241]
	v_pk_fma_f32 v[186:187], v[186:187], v[238:239], v[240:241]
	v_pk_mul_f32 v[184:185], v[176:177], v[184:185]
	v_pk_mul_f32 v[186:187], v[178:179], v[186:187]
	v_exp_f32_e32 v184, v184
	v_exp_f32_e32 v185, v185
	v_exp_f32_e32 v186, v186
	v_exp_f32_e32 v187, v187
	s_nop 0
	v_pk_add_f32 v[184:185], v[184:185], v[242:243]
	v_pk_add_f32 v[186:187], v[186:187], v[242:243]
	v_rcp_f32_e32 v184, v184
	v_rcp_f32_e32 v185, v185
	v_rcp_f32_e32 v186, v186
	v_rcp_f32_e32 v187, v187
	v_mad_i64_i32 v[168:169], s[0:1], v210, s88, v[246:247]
	v_pk_mul_f32 v[184:185], v[176:177], v[184:185]
	v_pk_mul_f32 v[186:187], v[178:179], v[186:187]
	v_pk_mul_f32 v[184:185], v[184:185], v[180:181]
	v_pk_mul_f32 v[186:187], v[186:187], v[182:183]
	v_mov_b32_e32 v188, v170
	v_mov_b32_e32 v189, v171
	v_cvt_pk_bf16_f32 v190, v184, v185
	v_cvt_pk_bf16_f32 v191, v186, v187
	global_store_dwordx4 v[168:169], v[188:191], off
	v_pk_fma_f32 v[176:177], v[28:29], v[152:153], v[156:157]
	v_pk_fma_f32 v[178:179], v[30:31], v[154:155], v[158:159]
	v_pk_fma_f32 v[180:181], v[20:21], v[136:137], v[140:141]
	v_pk_fma_f32 v[182:183], v[22:23], v[138:139], v[142:143]
	v_fmac_f32_dpp v176, v28, v148 row_shr:1 row_mask:0xf bank_mask:0xf bound_ctrl:1
	v_fmac_f32_dpp v177, v29, v149 row_shr:1 row_mask:0xf bank_mask:0xf bound_ctrl:1
	v_fmac_f32_dpp v178, v30, v150 row_shr:1 row_mask:0xf bank_mask:0xf bound_ctrl:1
	v_fmac_f32_dpp v179, v31, v151 row_shr:1 row_mask:0xf bank_mask:0xf bound_ctrl:1
	v_fmac_f32_dpp v176, v28, v144 row_shr:2 row_mask:0xf bank_mask:0xf bound_ctrl:1
	v_fmac_f32_dpp v177, v29, v145 row_shr:2 row_mask:0xf bank_mask:0xf bound_ctrl:1
	v_fmac_f32_dpp v178, v30, v146 row_shr:2 row_mask:0xf bank_mask:0xf bound_ctrl:1
	v_fmac_f32_dpp v179, v31, v147 row_shr:2 row_mask:0xf bank_mask:0xf bound_ctrl:1
	v_fmac_f32_dpp v176, v12, v148 row_shl:15 row_mask:0xf bank_mask:0xf bound_ctrl:1
	v_fmac_f32_dpp v177, v13, v149 row_shl:15 row_mask:0xf bank_mask:0xf bound_ctrl:1
	v_fmac_f32_dpp v178, v14, v150 row_shl:15 row_mask:0xf bank_mask:0xf bound_ctrl:1
	v_fmac_f32_dpp v179, v15, v151 row_shl:15 row_mask:0xf bank_mask:0xf bound_ctrl:1
	v_fmac_f32_dpp v176, v12, v144 row_shl:14 row_mask:0xf bank_mask:0xf bound_ctrl:1
	v_fmac_f32_dpp v177, v13, v145 row_shl:14 row_mask:0xf bank_mask:0xf bound_ctrl:1
	v_fmac_f32_dpp v178, v14, v146 row_shl:14 row_mask:0xf bank_mask:0xf bound_ctrl:1
	v_fmac_f32_dpp v179, v15, v147 row_shl:14 row_mask:0xf bank_mask:0xf bound_ctrl:1
	v_fmac_f32_dpp v180, v20, v132 row_shr:1 row_mask:0xf bank_mask:0xf bound_ctrl:1
; __device__ __forceinline__ unsigned cvt_pk_bf16(float lo, float hi) { const f32x2 v = {lo, hi}; return __builtin_bit_cast(unsigned, __builtin_convertvector(v, bf16x2_t)); }
;     __device__ __forceinline__ void operator()(Acc& acc, const Unit& u, int wr, int wc, int fr, int fq) const {
;     ...
;                 for (int m = 0; m < 4; ++m) {
;                     const f32x4 ca = acc[ai][0][m][n], cbv = acc[ai][1][m][n];
;                     const f32x4 pa = (m > 0) ? acc[ai][0][m > 0 ? m - 1 : 0][n] : ha, pb = (m > 0) ? acc[ai][1][m > 0 ? m - 1 : 0][n] : hb;
;                     float res[4];
; #pragma unroll
;                     for (int e = 0; e < 4; ++e) {
;                         const float a1 = dpp_prev1(ca[e], pa[e]), a2 = dpp_prev2(ca[e], pa[e]);
;                         const float b1 = dpp_prev1(cbv[e], pb[e]), b2 = dpp_prev2(cbv[e], pb[e]);
;                         const float ua = bba[e] + w0a[e] * a2 + w1a[e] * a1 + w2a[e] * ca[e];
;                         const float ub = bbb[e] + w0b[e] * b2 + w1b[e] * b1 + w2b[e] * cbv[e];
;                         res[e] = gelu_tanh(ua) * ub; }
;                     const int row = row0 + ai * HALF + m * 16;
;                     u32x2 w; w.x = cvt_pk_bf16(res[0], res[1]); w.y = cvt_pk_bf16(res[2], res[3]);
;                     *(u32x2*)(act + (size_t)row * FF + col) = w;
;                     asm volatile("" ::: "memory"); } } }
	v_fmac_f32_dpp v181, v21, v133 row_shr:1 row_mask:0xf bank_mask:0xf bound_ctrl:1
	v_fmac_f32_dpp v182, v22, v134 row_shr:1 row_mask:0xf bank_mask:0xf bound_ctrl:1
	v_fmac_f32_dpp v183, v23, v135 row_shr:1 row_mask:0xf bank_mask:0xf bound_ctrl:1
	v_fmac_f32_dpp v180, v20, v128 row_shr:2 row_mask:0xf bank_mask:0xf bound_ctrl:1
	v_fmac_f32_dpp v181, v21, v129 row_shr:2 row_mask:0xf bank_mask:0xf bound_ctrl:1
	v_fmac_f32_dpp v182, v22, v130 row_shr:2 row_mask:0xf bank_mask:0xf bound_ctrl:1
	v_fmac_f32_dpp v183, v23, v131 row_shr:2 row_mask:0xf bank_mask:0xf bound_ctrl:1
	v_fmac_f32_dpp v180, v4, v132 row_shl:15 row_mask:0xf bank_mask:0xf bound_ctrl:1
	v_fmac_f32_dpp v181, v5, v133 row_shl:15 row_mask:0xf bank_mask:0xf bound_ctrl:1
	v_fmac_f32_dpp v182, v6, v134 row_shl:15 row_mask:0xf bank_mask:0xf bound_ctrl:1
	v_fmac_f32_dpp v183, v7, v135 row_shl:15 row_mask:0xf bank_mask:0xf bound_ctrl:1
	v_fmac_f32_dpp v180, v4, v128 row_shl:14 row_mask:0xf bank_mask:0xf bound_ctrl:1
	v_fmac_f32_dpp v181, v5, v129 row_shl:14 row_mask:0xf bank_mask:0xf bound_ctrl:1
	v_fmac_f32_dpp v182, v6, v130 row_shl:14 row_mask:0xf bank_mask:0xf bound_ctrl:1
	v_fmac_f32_dpp v183, v7, v131 row_shl:14 row_mask:0xf bank_mask:0xf bound_ctrl:1
	v_pk_mul_f32 v[184:185], v[176:177], v[176:177]
	v_pk_mul_f32 v[186:187], v[178:179], v[178:179]
	v_pk_fma_f32 v[184:185], v[184:185], v[238:239], v[240:241]
	v_pk_fma_f32 v[186:187], v[186:187], v[238:239], v[240:241]
	v_pk_mul_f32 v[184:185], v[176:177], v[184:185]
	v_pk_mul_f32 v[186:187], v[178:179], v[186:187]
	v_exp_f32_e32 v184, v184
	v_exp_f32_e32 v185, v185
	v_exp_f32_e32 v186, v186
	v_exp_f32_e32 v187, v187
	s_nop 0
	v_pk_add_f32 v[184:185], v[184:185], v[242:243]
	v_pk_add_f32 v[186:187], v[186:187], v[242:243]
	v_rcp_f32_e32 v184, v184
	v_rcp_f32_e32 v185, v185
	v_rcp_f32_e32 v186, v186
	v_rcp_f32_e32 v187, v187
	v_mad_i64_i32 v[168:169], s[0:1], v220, s88, v[246:247]
	v_pk_mul_f32 v[184:185], v[176:177], v[184:185]
	v_pk_mul_f32 v[186:187], v[178:179], v[186:187]
	v_pk_mul_f32 v[184:185], v[184:185], v[180:181]
	v_pk_mul_f32 v[186:187], v[186:187], v[182:183]
	v_mov_b32_e32 v188, v172
	v_mov_b32_e32 v189, v173
	v_cvt_pk_bf16_f32 v190, v184, v185
	v_cvt_pk_bf16_f32 v191, v186, v187
	global_store_dwordx4 v[168:169], v[188:191], off
	v_pk_fma_f32 v[176:177], v[44:45], v[152:153], v[156:157]
	v_pk_fma_f32 v[178:179], v[46:47], v[154:155], v[158:159]
	v_pk_fma_f32 v[180:181], v[36:37], v[136:137], v[140:141]
	v_pk_fma_f32 v[182:183], v[38:39], v[138:139], v[142:143]
	v_fmac_f32_dpp v176, v44, v148 row_shr:1 row_mask:0xf bank_mask:0xf bound_ctrl:1
	v_fmac_f32_dpp v177, v45, v149 row_shr:1 row_mask:0xf bank_mask:0xf bound_ctrl:1
	v_fmac_f32_dpp v178, v46, v150 row_shr:1 row_mask:0xf bank_mask:0xf bound_ctrl:1
	v_fmac_f32_dpp v179, v47, v151 row_shr:1 row_mask:0xf bank_mask:0xf bound_ctrl:1
	v_fmac_f32_dpp v176, v44, v144 row_shr:2 row_mask:0xf bank_mask:0xf bound_ctrl:1
	v_fmac_f32_dpp v177, v45, v145 row_shr:2 row_mask:0xf bank_mask:0xf bound_ctrl:1
	v_fmac_f32_dpp v178, v46, v146 row_shr:2 row_mask:0xf bank_mask:0xf bound_ctrl:1
	v_fmac_f32_dpp v179, v47, v147 row_shr:2 row_mask:0xf bank_mask:0xf bound_ctrl:1
	v_fmac_f32_dpp v176, v28, v148 row_shl:15 row_mask:0xf bank_mask:0xf bound_ctrl:1
	v_fmac_f32_dpp v177, v29, v149 row_shl:15 row_mask:0xf bank_mask:0xf bound_ctrl:1
	v_fmac_f32_dpp v178, v30, v150 row_shl:15 row_mask:0xf bank_mask:0xf bound_ctrl:1
	v_fmac_f32_dpp v179, v31, v151 row_shl:15 row_mask:0xf bank_mask:0xf bound_ctrl:1
	v_fmac_f32_dpp v176, v28, v144 row_shl:14 row_mask:0xf bank_mask:0xf bound_ctrl:1
	v_fmac_f32_dpp v177, v29, v145 row_shl:14 row_mask:0xf bank_mask:0xf bound_ctrl:1
	v_fmac_f32_dpp v178, v30, v146 row_shl:14 row_mask:0xf bank_mask:0xf bound_ctrl:1
	v_fmac_f32_dpp v179, v31, v147 row_shl:14 row_mask:0xf bank_mask:0xf bound_ctrl:1
	v_fmac_f32_dpp v180, v36, v132 row_shr:1 row_mask:0xf bank_mask:0xf bound_ctrl:1
	v_fmac_f32_dpp v181, v37, v133 row_shr:1 row_mask:0xf bank_mask:0xf bound_ctrl:1
	v_fmac_f32_dpp v182, v38, v134 row_shr:1 row_mask:0xf bank_mask:0xf bound_ctrl:1
	v_fmac_f32_dpp v183, v39, v135 row_shr:1 row_mask:0xf bank_mask:0xf bound_ctrl:1
	v_fmac_f32_dpp v180, v36, v128 row_shr:2 row_mask:0xf bank_mask:0xf bound_ctrl:1
	v_fmac_f32_dpp v181, v37, v129 row_shr:2 row_mask:0xf bank_mask:0xf bound_ctrl:1
	v_fmac_f32_dpp v182, v38, v130 row_shr:2 row_mask:0xf bank_mask:0xf bound_ctrl:1
	v_fmac_f32_dpp v183, v39, v131 row_shr:2 row_mask:0xf bank_mask:0xf bound_ctrl:1
	v_fmac_f32_dpp v180, v20, v132 row_shl:15 row_mask:0xf bank_mask:0xf bound_ctrl:1
	v_fmac_f32_dpp v181, v21, v133 row_shl:15 row_mask:0xf bank_mask:0xf bound_ctrl:1
	v_fmac_f32_dpp v182, v22, v134 row_shl:15 row_mask:0xf bank_mask:0xf bound_ctrl:1
	v_fmac_f32_dpp v183, v23, v135 row_shl:15 row_mask:0xf bank_mask:0xf bound_ctrl:1
	v_fmac_f32_dpp v180, v20, v128 row_shl:14 row_mask:0xf bank_mask:0xf bound_ctrl:1
	v_fmac_f32_dpp v181, v21, v129 row_shl:14 row_mask:0xf bank_mask:0xf bound_ctrl:1
	v_fmac_f32_dpp v182, v22, v130 row_shl:14 row_mask:0xf bank_mask:0xf bound_ctrl:1
	v_fmac_f32_dpp v183, v23, v131 row_shl:14 row_mask:0xf bank_mask:0xf bound_ctrl:1
	v_pk_mul_f32 v[184:185], v[176:177], v[176:177]
	v_pk_mul_f32 v[186:187], v[178:179], v[178:179]
	v_pk_fma_f32 v[184:185], v[184:185], v[238:239], v[240:241]
	v_pk_fma_f32 v[186:187], v[186:187], v[238:239], v[240:241]
	v_pk_mul_f32 v[184:185], v[176:177], v[184:185]
	v_pk_mul_f32 v[186:187], v[178:179], v[186:187]
	v_exp_f32_e32 v184, v184
	v_exp_f32_e32 v185, v185
	v_exp_f32_e32 v186, v186
	v_exp_f32_e32 v187, v187
	s_nop 0
	v_pk_add_f32 v[184:185], v[184:185], v[242:243]
; #define LAS __attribute__((address_space(3)))
; __device__ __forceinline__ unsigned cvt_pk_bf16(float lo, float hi) { const f32x2 v = {lo, hi}; return __builtin_bit_cast(unsigned, __builtin_convertvector(v, bf16x2_t)); }
;     __device__ __forceinline__ void operator()(Acc& acc, const Unit& u, int wr, int wc, int fr, int fq) const {
;     ...
;             for (int ai = 0; ai < 2; ++ai) {
;                 const int s = ai * 2 + wr;
;                 f32x4 ha = (f32x4){0.f, 0.f, 0.f, 0.f}, hb = ha;
;                 if (s > 0 && fr >= 14) { ha = *(const LAS f32x4*)(halo + (((s - 1) * 2 + (fr - 14)) * 2 + 0) * HALF + cl + 4 * n);
;                                           hb = *(const LAS f32x4*)(halo + (((s - 1) * 2 + (fr - 14)) * 2 + 1) * HALF + cl + 4 * n); }
; #pragma unroll
;                 for (int m = 0; m < 4; ++m) {
;                     const f32x4 ca = acc[ai][0][m][n], cbv = acc[ai][1][m][n];
;                     const f32x4 pa = (m > 0) ? acc[ai][0][m > 0 ? m - 1 : 0][n] : ha, pb = (m > 0) ? acc[ai][1][m > 0 ? m - 1 : 0][n] : hb;
;                     float res[4];
; #pragma unroll
;                     for (int e = 0; e < 4; ++e) {
;                         const float a1 = dpp_prev1(ca[e], pa[e]), a2 = dpp_prev2(ca[e], pa[e]);
;                         const float b1 = dpp_prev1(cbv[e], pb[e]), b2 = dpp_prev2(cbv[e], pb[e]);
;                         const float ua = bba[e] + w0a[e] * a2 + w1a[e] * a1 + w2a[e] * ca[e];
;                         const float ub = bbb[e] + w0b[e] * b2 + w1b[e] * b1 + w2b[e] * cbv[e];
;                         res[e] = gelu_tanh(ua) * ub; }
;                     const int row = row0 + ai * HALF + m * 16;
;                     u32x2 w; w.x = cvt_pk_bf16(res[0], res[1]); w.y = cvt_pk_bf16(res[2], res[3]);
;                     *(u32x2*)(act + (size_t)row * FF + col) = w;
;                     asm volatile("" ::: "memory"); } } }
	v_pk_add_f32 v[186:187], v[186:187], v[242:243]
	v_rcp_f32_e32 v184, v184
	v_rcp_f32_e32 v185, v185
	v_rcp_f32_e32 v186, v186
	v_rcp_f32_e32 v187, v187
	v_mad_i64_i32 v[168:169], s[0:1], v214, s88, v[246:247]
	v_pk_mul_f32 v[184:185], v[176:177], v[184:185]
	v_pk_mul_f32 v[186:187], v[178:179], v[186:187]
	v_pk_mul_f32 v[184:185], v[184:185], v[180:181]
	v_pk_mul_f32 v[186:187], v[186:187], v[182:183]
	v_mov_b32_e32 v188, v174
	v_mov_b32_e32 v189, v175
	v_cvt_pk_bf16_f32 v190, v184, v185
	v_cvt_pk_bf16_f32 v191, v186, v187
	global_store_dwordx4 v[168:169], v[188:191], off
	v_pk_fma_f32 v[176:177], v[60:61], v[152:153], v[156:157]
	v_pk_fma_f32 v[178:179], v[62:63], v[154:155], v[158:159]
	v_pk_fma_f32 v[180:181], v[52:53], v[136:137], v[140:141]
	v_pk_fma_f32 v[182:183], v[54:55], v[138:139], v[142:143]
	v_fmac_f32_dpp v176, v60, v148 row_shr:1 row_mask:0xf bank_mask:0xf bound_ctrl:1
	v_fmac_f32_dpp v177, v61, v149 row_shr:1 row_mask:0xf bank_mask:0xf bound_ctrl:1
	v_fmac_f32_dpp v178, v62, v150 row_shr:1 row_mask:0xf bank_mask:0xf bound_ctrl:1
	v_fmac_f32_dpp v179, v63, v151 row_shr:1 row_mask:0xf bank_mask:0xf bound_ctrl:1
	v_fmac_f32_dpp v176, v60, v144 row_shr:2 row_mask:0xf bank_mask:0xf bound_ctrl:1
	v_fmac_f32_dpp v177, v61, v145 row_shr:2 row_mask:0xf bank_mask:0xf bound_ctrl:1
	v_fmac_f32_dpp v178, v62, v146 row_shr:2 row_mask:0xf bank_mask:0xf bound_ctrl:1
	v_fmac_f32_dpp v179, v63, v147 row_shr:2 row_mask:0xf bank_mask:0xf bound_ctrl:1
	v_fmac_f32_dpp v176, v44, v148 row_shl:15 row_mask:0xf bank_mask:0xf bound_ctrl:1
	v_fmac_f32_dpp v177, v45, v149 row_shl:15 row_mask:0xf bank_mask:0xf bound_ctrl:1
	v_fmac_f32_dpp v178, v46, v150 row_shl:15 row_mask:0xf bank_mask:0xf bound_ctrl:1
	v_fmac_f32_dpp v179, v47, v151 row_shl:15 row_mask:0xf bank_mask:0xf bound_ctrl:1
	v_fmac_f32_dpp v176, v44, v144 row_shl:14 row_mask:0xf bank_mask:0xf bound_ctrl:1
	v_fmac_f32_dpp v177, v45, v145 row_shl:14 row_mask:0xf bank_mask:0xf bound_ctrl:1
	v_fmac_f32_dpp v178, v46, v146 row_shl:14 row_mask:0xf bank_mask:0xf bound_ctrl:1
	v_fmac_f32_dpp v179, v47, v147 row_shl:14 row_mask:0xf bank_mask:0xf bound_ctrl:1
	v_fmac_f32_dpp v180, v52, v132 row_shr:1 row_mask:0xf bank_mask:0xf bound_ctrl:1
	v_fmac_f32_dpp v181, v53, v133 row_shr:1 row_mask:0xf bank_mask:0xf bound_ctrl:1
	v_fmac_f32_dpp v182, v54, v134 row_shr:1 row_mask:0xf bank_mask:0xf bound_ctrl:1
	v_fmac_f32_dpp v183, v55, v135 row_shr:1 row_mask:0xf bank_mask:0xf bound_ctrl:1
	v_fmac_f32_dpp v180, v52, v128 row_shr:2 row_mask:0xf bank_mask:0xf bound_ctrl:1
	v_fmac_f32_dpp v181, v53, v129 row_shr:2 row_mask:0xf bank_mask:0xf bound_ctrl:1
	v_fmac_f32_dpp v182, v54, v130 row_shr:2 row_mask:0xf bank_mask:0xf bound_ctrl:1
	v_fmac_f32_dpp v183, v55, v131 row_shr:2 row_mask:0xf bank_mask:0xf bound_ctrl:1
	v_fmac_f32_dpp v180, v36, v132 row_shl:15 row_mask:0xf bank_mask:0xf bound_ctrl:1
	v_fmac_f32_dpp v181, v37, v133 row_shl:15 row_mask:0xf bank_mask:0xf bound_ctrl:1
	v_fmac_f32_dpp v182, v38, v134 row_shl:15 row_mask:0xf bank_mask:0xf bound_ctrl:1
	v_fmac_f32_dpp v183, v39, v135 row_shl:15 row_mask:0xf bank_mask:0xf bound_ctrl:1
	v_fmac_f32_dpp v180, v36, v128 row_shl:14 row_mask:0xf bank_mask:0xf bound_ctrl:1
	v_fmac_f32_dpp v181, v37, v129 row_shl:14 row_mask:0xf bank_mask:0xf bound_ctrl:1
	v_fmac_f32_dpp v182, v38, v130 row_shl:14 row_mask:0xf bank_mask:0xf bound_ctrl:1
	v_fmac_f32_dpp v183, v39, v131 row_shl:14 row_mask:0xf bank_mask:0xf bound_ctrl:1
	v_pk_mul_f32 v[184:185], v[176:177], v[176:177]
	v_pk_mul_f32 v[186:187], v[178:179], v[178:179]
	v_pk_fma_f32 v[184:185], v[184:185], v[238:239], v[240:241]
	v_pk_fma_f32 v[186:187], v[186:187], v[238:239], v[240:241]
	v_pk_mul_f32 v[184:185], v[176:177], v[184:185]
	v_pk_mul_f32 v[186:187], v[178:179], v[186:187]
	v_exp_f32_e32 v184, v184
	v_exp_f32_e32 v185, v185
	v_exp_f32_e32 v186, v186
	v_exp_f32_e32 v187, v187
	s_nop 0
	v_pk_add_f32 v[184:185], v[184:185], v[242:243]
	v_pk_add_f32 v[186:187], v[186:187], v[242:243]
	v_rcp_f32_e32 v184, v184
	v_rcp_f32_e32 v185, v185
	v_rcp_f32_e32 v186, v186
	v_rcp_f32_e32 v187, v187
	v_mad_i64_i32 v[168:169], s[0:1], v212, s88, v[246:247]
	v_pk_mul_f32 v[184:185], v[176:177], v[184:185]
	v_pk_mul_f32 v[186:187], v[178:179], v[186:187]
	v_pk_mul_f32 v[184:185], v[184:185], v[180:181]
	v_pk_mul_f32 v[186:187], v[186:187], v[182:183]
	v_mov_b32_e32 v188, v237
	v_mov_b32_e32 v189, v248
	v_cvt_pk_bf16_f32 v190, v184, v185
	v_cvt_pk_bf16_f32 v191, v186, v187
	global_store_dwordx4 v[168:169], v[188:191], off
	v_mov_b32_e32 v160, 0
	v_mov_b32_e32 v161, 0
	v_mov_b32_e32 v162, 0
	v_mov_b32_e32 v163, 0
	v_mov_b32_e32 v164, 0
	v_mov_b32_e32 v165, 0
	v_mov_b32_e32 v166, 0
	v_mov_b32_e32 v167, 0
	s_and_b64 s[42:43], s[28:29], s[6:7]
	s_and_saveexec_b64 s[56:57], s[42:43]
	s_cbranch_execz .Lcv_h11
	v_add_u32_e32 v168, 0xffffd010, v244
	v_add_u32_e32 v169, 0xffffd210, v244
	ds_read_b128 v[160:163], v168
	ds_read_b128 v[164:167], v169
; #define LAS __attribute__((address_space(3)))
; __device__ __forceinline__ unsigned cvt_pk_bf16(float lo, float hi) { const f32x2 v = {lo, hi}; return __builtin_bit_cast(unsigned, __builtin_convertvector(v, bf16x2_t)); }
;     __device__ __forceinline__ void operator()(Acc& acc, const Unit& u, int wr, int wc, int fr, int fq) const {
;     ...
;             for (int ai = 0; ai < 2; ++ai) {
;                 const int s = ai * 2 + wr;
;                 f32x4 ha = (f32x4){0.f, 0.f, 0.f, 0.f}, hb = ha;
;                 if (s > 0 && fr >= 14) { ha = *(const LAS f32x4*)(halo + (((s - 1) * 2 + (fr - 14)) * 2 + 0) * HALF + cl + 4 * n);
;                                           hb = *(const LAS f32x4*)(halo + (((s - 1) * 2 + (fr - 14)) * 2 + 1) * HALF + cl + 4 * n); }
; #pragma unroll
;                 for (int m = 0; m < 4; ++m) {
;                     const f32x4 ca = acc[ai][0][m][n], cbv = acc[ai][1][m][n];
;                     const f32x4 pa = (m > 0) ? acc[ai][0][m > 0 ? m - 1 : 0][n] : ha, pb = (m > 0) ? acc[ai][1][m > 0 ? m - 1 : 0][n] : hb;
;                     float res[4];
; #pragma unroll
;                     for (int e = 0; e < 4; ++e) {
;                         const float a1 = dpp_prev1(ca[e], pa[e]), a2 = dpp_prev2(ca[e], pa[e]);
;                         const float b1 = dpp_prev1(cbv[e], pb[e]), b2 = dpp_prev2(cbv[e], pb[e]);
;                         const float ua = bba[e] + w0a[e] * a2 + w1a[e] * a1 + w2a[e] * ca[e];
;                         const float ub = bbb[e] + w0b[e] * b2 + w1b[e] * b1 + w2b[e] * cbv[e];
;                         res[e] = gelu_tanh(ua) * ub; }
;                     const int row = row0 + ai * HALF + m * 16;
;                     u32x2 w; w.x = cvt_pk_bf16(res[0], res[1]); w.y = cvt_pk_bf16(res[2], res[3]);
;                     *(u32x2*)(act + (size_t)row * FF + col) = w;
;                     asm volatile("" ::: "memory"); } } }
.Lcv_h11:
	s_or_b64 exec, exec, s[56:57]
	s_waitcnt lgkmcnt(0)
	v_pk_fma_f32 v[176:177], v[68:69], v[152:153], v[156:157]
	v_pk_fma_f32 v[178:179], v[70:71], v[154:155], v[158:159]
	v_pk_fma_f32 v[180:181], v[76:77], v[136:137], v[140:141]
	v_pk_fma_f32 v[182:183], v[78:79], v[138:139], v[142:143]
	v_fmac_f32_dpp v176, v68, v148 row_shr:1 row_mask:0xf bank_mask:0xf bound_ctrl:1
	v_fmac_f32_dpp v177, v69, v149 row_shr:1 row_mask:0xf bank_mask:0xf bound_ctrl:1
	v_fmac_f32_dpp v178, v70, v150 row_shr:1 row_mask:0xf bank_mask:0xf bound_ctrl:1
	v_fmac_f32_dpp v179, v71, v151 row_shr:1 row_mask:0xf bank_mask:0xf bound_ctrl:1
	v_fmac_f32_dpp v176, v68, v144 row_shr:2 row_mask:0xf bank_mask:0xf bound_ctrl:1
	v_fmac_f32_dpp v177, v69, v145 row_shr:2 row_mask:0xf bank_mask:0xf bound_ctrl:1
	v_fmac_f32_dpp v178, v70, v146 row_shr:2 row_mask:0xf bank_mask:0xf bound_ctrl:1
	v_fmac_f32_dpp v179, v71, v147 row_shr:2 row_mask:0xf bank_mask:0xf bound_ctrl:1
	v_fmac_f32_dpp v176, v160, v148 row_shl:15 row_mask:0xf bank_mask:0xf bound_ctrl:1
	v_fmac_f32_dpp v177, v161, v149 row_shl:15 row_mask:0xf bank_mask:0xf bound_ctrl:1
	v_fmac_f32_dpp v178, v162, v150 row_shl:15 row_mask:0xf bank_mask:0xf bound_ctrl:1
	v_fmac_f32_dpp v179, v163, v151 row_shl:15 row_mask:0xf bank_mask:0xf bound_ctrl:1
	v_fmac_f32_dpp v176, v160, v144 row_shl:14 row_mask:0xf bank_mask:0xf bound_ctrl:1
	v_fmac_f32_dpp v177, v161, v145 row_shl:14 row_mask:0xf bank_mask:0xf bound_ctrl:1
	v_fmac_f32_dpp v178, v162, v146 row_shl:14 row_mask:0xf bank_mask:0xf bound_ctrl:1
	v_fmac_f32_dpp v179, v163, v147 row_shl:14 row_mask:0xf bank_mask:0xf bound_ctrl:1
	v_fmac_f32_dpp v180, v76, v132 row_shr:1 row_mask:0xf bank_mask:0xf bound_ctrl:1
	v_fmac_f32_dpp v181, v77, v133 row_shr:1 row_mask:0xf bank_mask:0xf bound_ctrl:1
	v_fmac_f32_dpp v182, v78, v134 row_shr:1 row_mask:0xf bank_mask:0xf bound_ctrl:1
	v_fmac_f32_dpp v183, v79, v135 row_shr:1 row_mask:0xf bank_mask:0xf bound_ctrl:1
	v_fmac_f32_dpp v180, v76, v128 row_shr:2 row_mask:0xf bank_mask:0xf bound_ctrl:1
	v_fmac_f32_dpp v181, v77, v129 row_shr:2 row_mask:0xf bank_mask:0xf bound_ctrl:1
	v_fmac_f32_dpp v182, v78, v130 row_shr:2 row_mask:0xf bank_mask:0xf bound_ctrl:1
	v_fmac_f32_dpp v183, v79, v131 row_shr:2 row_mask:0xf bank_mask:0xf bound_ctrl:1
	v_fmac_f32_dpp v180, v164, v132 row_shl:15 row_mask:0xf bank_mask:0xf bound_ctrl:1
	v_fmac_f32_dpp v181, v165, v133 row_shl:15 row_mask:0xf bank_mask:0xf bound_ctrl:1
	v_fmac_f32_dpp v182, v166, v134 row_shl:15 row_mask:0xf bank_mask:0xf bound_ctrl:1
	v_fmac_f32_dpp v183, v167, v135 row_shl:15 row_mask:0xf bank_mask:0xf bound_ctrl:1
	v_fmac_f32_dpp v180, v164, v128 row_shl:14 row_mask:0xf bank_mask:0xf bound_ctrl:1
	v_fmac_f32_dpp v181, v165, v129 row_shl:14 row_mask:0xf bank_mask:0xf bound_ctrl:1
	v_fmac_f32_dpp v182, v166, v130 row_shl:14 row_mask:0xf bank_mask:0xf bound_ctrl:1
	v_fmac_f32_dpp v183, v167, v131 row_shl:14 row_mask:0xf bank_mask:0xf bound_ctrl:1
	v_pk_mul_f32 v[184:185], v[176:177], v[176:177]
	v_pk_mul_f32 v[186:187], v[178:179], v[178:179]
	v_pk_fma_f32 v[184:185], v[184:185], v[238:239], v[240:241]
	v_pk_fma_f32 v[186:187], v[186:187], v[238:239], v[240:241]
	v_pk_mul_f32 v[184:185], v[176:177], v[184:185]
	v_pk_mul_f32 v[186:187], v[178:179], v[186:187]
	v_exp_f32_e32 v184, v184
	v_exp_f32_e32 v185, v185
	v_exp_f32_e32 v186, v186
	v_exp_f32_e32 v187, v187
	s_nop 0
	v_pk_add_f32 v[184:185], v[184:185], v[242:243]
	v_pk_add_f32 v[186:187], v[186:187], v[242:243]
	v_rcp_f32_e32 v184, v184
	v_rcp_f32_e32 v185, v185
	v_rcp_f32_e32 v186, v186
	v_rcp_f32_e32 v187, v187
	v_mad_i64_i32 v[168:169], s[0:1], v224, s88, v[246:247]
	v_pk_mul_f32 v[184:185], v[176:177], v[184:185]
	v_pk_mul_f32 v[186:187], v[178:179], v[186:187]
	v_pk_mul_f32 v[184:185], v[184:185], v[180:181]
	v_pk_mul_f32 v[186:187], v[186:187], v[182:183]
	v_mov_b32_e32 v188, v249
	v_mov_b32_e32 v189, v250
	v_cvt_pk_bf16_f32 v190, v184, v185
	v_cvt_pk_bf16_f32 v191, v186, v187
	global_store_dwordx4 v[168:169], v[188:191], off
	v_pk_fma_f32 v[176:177], v[84:85], v[152:153], v[156:157]
	v_pk_fma_f32 v[178:179], v[86:87], v[154:155], v[158:159]
	v_pk_fma_f32 v[180:181], v[92:93], v[136:137], v[140:141]
	v_pk_fma_f32 v[182:183], v[94:95], v[138:139], v[142:143]
	v_fmac_f32_dpp v176, v84, v148 row_shr:1 row_mask:0xf bank_mask:0xf bound_ctrl:1
	v_fmac_f32_dpp v177, v85, v149 row_shr:1 row_mask:0xf bank_mask:0xf bound_ctrl:1
	v_fmac_f32_dpp v178, v86, v150 row_shr:1 row_mask:0xf bank_mask:0xf bound_ctrl:1
	v_fmac_f32_dpp v179, v87, v151 row_shr:1 row_mask:0xf bank_mask:0xf bound_ctrl:1
	v_fmac_f32_dpp v176, v84, v144 row_shr:2 row_mask:0xf bank_mask:0xf bound_ctrl:1
	v_fmac_f32_dpp v177, v85, v145 row_shr:2 row_mask:0xf bank_mask:0xf bound_ctrl:1
	v_fmac_f32_dpp v178, v86, v146 row_shr:2 row_mask:0xf bank_mask:0xf bound_ctrl:1
	v_fmac_f32_dpp v179, v87, v147 row_shr:2 row_mask:0xf bank_mask:0xf bound_ctrl:1
	v_fmac_f32_dpp v176, v68, v148 row_shl:15 row_mask:0xf bank_mask:0xf bound_ctrl:1
	v_fmac_f32_dpp v177, v69, v149 row_shl:15 row_mask:0xf bank_mask:0xf bound_ctrl:1
	v_fmac_f32_dpp v178, v70, v150 row_shl:15 row_mask:0xf bank_mask:0xf bound_ctrl:1
	v_fmac_f32_dpp v179, v71, v151 row_shl:15 row_mask:0xf bank_mask:0xf bound_ctrl:1
	v_fmac_f32_dpp v176, v68, v144 row_shl:14 row_mask:0xf bank_mask:0xf bound_ctrl:1
	v_fmac_f32_dpp v177, v69, v145 row_shl:14 row_mask:0xf bank_mask:0xf bound_ctrl:1
	v_fmac_f32_dpp v178, v70, v146 row_shl:14 row_mask:0xf bank_mask:0xf bound_ctrl:1
	v_fmac_f32_dpp v179, v71, v147 row_shl:14 row_mask:0xf bank_mask:0xf bound_ctrl:1
	v_fmac_f32_dpp v180, v92, v132 row_shr:1 row_mask:0xf bank_mask:0xf bound_ctrl:1
; __device__ __forceinline__ unsigned cvt_pk_bf16(float lo, float hi) { const f32x2 v = {lo, hi}; return __builtin_bit_cast(unsigned, __builtin_convertvector(v, bf16x2_t)); }
;     __device__ __forceinline__ void operator()(Acc& acc, const Unit& u, int wr, int wc, int fr, int fq) const {
;     ...
;                 for (int m = 0; m < 4; ++m) {
;                     const f32x4 ca = acc[ai][0][m][n], cbv = acc[ai][1][m][n];
;                     const f32x4 pa = (m > 0) ? acc[ai][0][m > 0 ? m - 1 : 0][n] : ha, pb = (m > 0) ? acc[ai][1][m > 0 ? m - 1 : 0][n] : hb;
;                     float res[4];
; #pragma unroll
;                     for (int e = 0; e < 4; ++e) {
;                         const float a1 = dpp_prev1(ca[e], pa[e]), a2 = dpp_prev2(ca[e], pa[e]);
;                         const float b1 = dpp_prev1(cbv[e], pb[e]), b2 = dpp_prev2(cbv[e], pb[e]);
;                         const float ua = bba[e] + w0a[e] * a2 + w1a[e] * a1 + w2a[e] * ca[e];
;                         const float ub = bbb[e] + w0b[e] * b2 + w1b[e] * b1 + w2b[e] * cbv[e];
;                         res[e] = gelu_tanh(ua) * ub; }
;                     const int row = row0 + ai * HALF + m * 16;
;                     u32x2 w; w.x = cvt_pk_bf16(res[0], res[1]); w.y = cvt_pk_bf16(res[2], res[3]);
;                     *(u32x2*)(act + (size_t)row * FF + col) = w;
;                     asm volatile("" ::: "memory"); } } }
	v_fmac_f32_dpp v181, v93, v133 row_shr:1 row_mask:0xf bank_mask:0xf bound_ctrl:1
	v_fmac_f32_dpp v182, v94, v134 row_shr:1 row_mask:0xf bank_mask:0xf bound_ctrl:1
	v_fmac_f32_dpp v183, v95, v135 row_shr:1 row_mask:0xf bank_mask:0xf bound_ctrl:1
	v_fmac_f32_dpp v180, v92, v128 row_shr:2 row_mask:0xf bank_mask:0xf bound_ctrl:1
	v_fmac_f32_dpp v181, v93, v129 row_shr:2 row_mask:0xf bank_mask:0xf bound_ctrl:1
	v_fmac_f32_dpp v182, v94, v130 row_shr:2 row_mask:0xf bank_mask:0xf bound_ctrl:1
	v_fmac_f32_dpp v183, v95, v131 row_shr:2 row_mask:0xf bank_mask:0xf bound_ctrl:1
	v_fmac_f32_dpp v180, v76, v132 row_shl:15 row_mask:0xf bank_mask:0xf bound_ctrl:1
	v_fmac_f32_dpp v181, v77, v133 row_shl:15 row_mask:0xf bank_mask:0xf bound_ctrl:1
	v_fmac_f32_dpp v182, v78, v134 row_shl:15 row_mask:0xf bank_mask:0xf bound_ctrl:1
	v_fmac_f32_dpp v183, v79, v135 row_shl:15 row_mask:0xf bank_mask:0xf bound_ctrl:1
	v_fmac_f32_dpp v180, v76, v128 row_shl:14 row_mask:0xf bank_mask:0xf bound_ctrl:1
	v_fmac_f32_dpp v181, v77, v129 row_shl:14 row_mask:0xf bank_mask:0xf bound_ctrl:1
	v_fmac_f32_dpp v182, v78, v130 row_shl:14 row_mask:0xf bank_mask:0xf bound_ctrl:1
	v_fmac_f32_dpp v183, v79, v131 row_shl:14 row_mask:0xf bank_mask:0xf bound_ctrl:1
	v_pk_mul_f32 v[184:185], v[176:177], v[176:177]
	v_pk_mul_f32 v[186:187], v[178:179], v[178:179]
	v_pk_fma_f32 v[184:185], v[184:185], v[238:239], v[240:241]
	v_pk_fma_f32 v[186:187], v[186:187], v[238:239], v[240:241]
	v_pk_mul_f32 v[184:185], v[176:177], v[184:185]
	v_pk_mul_f32 v[186:187], v[178:179], v[186:187]
	v_exp_f32_e32 v184, v184
	v_exp_f32_e32 v185, v185
	v_exp_f32_e32 v186, v186
	v_exp_f32_e32 v187, v187
	s_nop 0
	v_pk_add_f32 v[184:185], v[184:185], v[242:243]
	v_pk_add_f32 v[186:187], v[186:187], v[242:243]
	v_rcp_f32_e32 v184, v184
	v_rcp_f32_e32 v185, v185
	v_rcp_f32_e32 v186, v186
	v_rcp_f32_e32 v187, v187
	v_mad_i64_i32 v[168:169], s[0:1], v218, s88, v[246:247]
	v_pk_mul_f32 v[184:185], v[176:177], v[184:185]
	v_pk_mul_f32 v[186:187], v[178:179], v[186:187]
	v_pk_mul_f32 v[184:185], v[184:185], v[180:181]
	v_pk_mul_f32 v[186:187], v[186:187], v[182:183]
	v_mov_b32_e32 v188, v251
	v_mov_b32_e32 v189, v211
	v_cvt_pk_bf16_f32 v190, v184, v185
	v_cvt_pk_bf16_f32 v191, v186, v187
	global_store_dwordx4 v[168:169], v[188:191], off
	v_pk_fma_f32 v[176:177], v[100:101], v[152:153], v[156:157]
	v_pk_fma_f32 v[178:179], v[102:103], v[154:155], v[158:159]
	v_pk_fma_f32 v[180:181], v[108:109], v[136:137], v[140:141]
	v_pk_fma_f32 v[182:183], v[110:111], v[138:139], v[142:143]
	v_fmac_f32_dpp v176, v100, v148 row_shr:1 row_mask:0xf bank_mask:0xf bound_ctrl:1
	v_fmac_f32_dpp v177, v101, v149 row_shr:1 row_mask:0xf bank_mask:0xf bound_ctrl:1
	v_fmac_f32_dpp v178, v102, v150 row_shr:1 row_mask:0xf bank_mask:0xf bound_ctrl:1
	v_fmac_f32_dpp v179, v103, v151 row_shr:1 row_mask:0xf bank_mask:0xf bound_ctrl:1
	v_fmac_f32_dpp v176, v100, v144 row_shr:2 row_mask:0xf bank_mask:0xf bound_ctrl:1
	v_fmac_f32_dpp v177, v101, v145 row_shr:2 row_mask:0xf bank_mask:0xf bound_ctrl:1
	v_fmac_f32_dpp v178, v102, v146 row_shr:2 row_mask:0xf bank_mask:0xf bound_ctrl:1
	v_fmac_f32_dpp v179, v103, v147 row_shr:2 row_mask:0xf bank_mask:0xf bound_ctrl:1
	v_fmac_f32_dpp v176, v84, v148 row_shl:15 row_mask:0xf bank_mask:0xf bound_ctrl:1
	v_fmac_f32_dpp v177, v85, v149 row_shl:15 row_mask:0xf bank_mask:0xf bound_ctrl:1
	v_fmac_f32_dpp v178, v86, v150 row_shl:15 row_mask:0xf bank_mask:0xf bound_ctrl:1
	v_fmac_f32_dpp v179, v87, v151 row_shl:15 row_mask:0xf bank_mask:0xf bound_ctrl:1
	v_fmac_f32_dpp v176, v84, v144 row_shl:14 row_mask:0xf bank_mask:0xf bound_ctrl:1
	v_fmac_f32_dpp v177, v85, v145 row_shl:14 row_mask:0xf bank_mask:0xf bound_ctrl:1
	v_fmac_f32_dpp v178, v86, v146 row_shl:14 row_mask:0xf bank_mask:0xf bound_ctrl:1
	v_fmac_f32_dpp v179, v87, v147 row_shl:14 row_mask:0xf bank_mask:0xf bound_ctrl:1
	v_fmac_f32_dpp v180, v108, v132 row_shr:1 row_mask:0xf bank_mask:0xf bound_ctrl:1
	v_fmac_f32_dpp v181, v109, v133 row_shr:1 row_mask:0xf bank_mask:0xf bound_ctrl:1
	v_fmac_f32_dpp v182, v110, v134 row_shr:1 row_mask:0xf bank_mask:0xf bound_ctrl:1
	v_fmac_f32_dpp v183, v111, v135 row_shr:1 row_mask:0xf bank_mask:0xf bound_ctrl:1
	v_fmac_f32_dpp v180, v108, v128 row_shr:2 row_mask:0xf bank_mask:0xf bound_ctrl:1
	v_fmac_f32_dpp v181, v109, v129 row_shr:2 row_mask:0xf bank_mask:0xf bound_ctrl:1
	v_fmac_f32_dpp v182, v110, v130 row_shr:2 row_mask:0xf bank_mask:0xf bound_ctrl:1
	v_fmac_f32_dpp v183, v111, v131 row_shr:2 row_mask:0xf bank_mask:0xf bound_ctrl:1
	v_fmac_f32_dpp v180, v92, v132 row_shl:15 row_mask:0xf bank_mask:0xf bound_ctrl:1
	v_fmac_f32_dpp v181, v93, v133 row_shl:15 row_mask:0xf bank_mask:0xf bound_ctrl:1
	v_fmac_f32_dpp v182, v94, v134 row_shl:15 row_mask:0xf bank_mask:0xf bound_ctrl:1
	v_fmac_f32_dpp v183, v95, v135 row_shl:15 row_mask:0xf bank_mask:0xf bound_ctrl:1
	v_fmac_f32_dpp v180, v92, v128 row_shl:14 row_mask:0xf bank_mask:0xf bound_ctrl:1
	v_fmac_f32_dpp v181, v93, v129 row_shl:14 row_mask:0xf bank_mask:0xf bound_ctrl:1
	v_fmac_f32_dpp v182, v94, v130 row_shl:14 row_mask:0xf bank_mask:0xf bound_ctrl:1
; __device__ __forceinline__ unsigned cvt_pk_bf16(float lo, float hi) { const f32x2 v = {lo, hi}; return __builtin_bit_cast(unsigned, __builtin_convertvector(v, bf16x2_t)); }
;     __device__ __forceinline__ void operator()(Acc& acc, const Unit& u, int wr, int wc, int fr, int fq) const {
;     ...
;                 for (int m = 0; m < 4; ++m) {
;                     const f32x4 ca = acc[ai][0][m][n], cbv = acc[ai][1][m][n];
;                     const f32x4 pa = (m > 0) ? acc[ai][0][m > 0 ? m - 1 : 0][n] : ha, pb = (m > 0) ? acc[ai][1][m > 0 ? m - 1 : 0][n] : hb;
;                     float res[4];
; #pragma unroll
;                     for (int e = 0; e < 4; ++e) {
;                         const float a1 = dpp_prev1(ca[e], pa[e]), a2 = dpp_prev2(ca[e], pa[e]);
;                         const float b1 = dpp_prev1(cbv[e], pb[e]), b2 = dpp_prev2(cbv[e], pb[e]);
;                         const float ua = bba[e] + w0a[e] * a2 + w1a[e] * a1 + w2a[e] * ca[e];
;                         const float ub = bbb[e] + w0b[e] * b2 + w1b[e] * b1 + w2b[e] * cbv[e];
;                         res[e] = gelu_tanh(ua) * ub; }
;                     const int row = row0 + ai * HALF + m * 16;
;                     u32x2 w; w.x = cvt_pk_bf16(res[0], res[1]); w.y = cvt_pk_bf16(res[2], res[3]);
;                     *(u32x2*)(act + (size_t)row * FF + col) = w;
;                     asm volatile("" ::: "memory"); } } }
	v_fmac_f32_dpp v183, v95, v131 row_shl:14 row_mask:0xf bank_mask:0xf bound_ctrl:1
	v_pk_mul_f32 v[184:185], v[176:177], v[176:177]
	v_pk_mul_f32 v[186:187], v[178:179], v[178:179]
	v_pk_fma_f32 v[184:185], v[184:185], v[238:239], v[240:241]
	v_pk_fma_f32 v[186:187], v[186:187], v[238:239], v[240:241]
	v_pk_mul_f32 v[184:185], v[176:177], v[184:185]
	v_pk_mul_f32 v[186:187], v[178:179], v[186:187]
	v_exp_f32_e32 v184, v184
	v_exp_f32_e32 v185, v185
	v_exp_f32_e32 v186, v186
	v_exp_f32_e32 v187, v187
	s_nop 0
	v_pk_add_f32 v[184:185], v[184:185], v[242:243]
	v_pk_add_f32 v[186:187], v[186:187], v[242:243]
	v_rcp_f32_e32 v184, v184
	v_rcp_f32_e32 v185, v185
	v_rcp_f32_e32 v186, v186
	v_rcp_f32_e32 v187, v187
	v_mad_i64_i32 v[168:169], s[0:1], v222, s88, v[246:247]
	v_pk_mul_f32 v[184:185], v[176:177], v[184:185]
	v_pk_mul_f32 v[186:187], v[178:179], v[186:187]
	v_pk_mul_f32 v[184:185], v[184:185], v[180:181]
	v_pk_mul_f32 v[186:187], v[186:187], v[182:183]
	v_mov_b32_e32 v188, v213
	v_mov_b32_e32 v189, v215
	v_cvt_pk_bf16_f32 v190, v184, v185
	v_cvt_pk_bf16_f32 v191, v186, v187
	global_store_dwordx4 v[168:169], v[188:191], off
	v_pk_fma_f32 v[176:177], v[116:117], v[152:153], v[156:157]
	v_pk_fma_f32 v[178:179], v[118:119], v[154:155], v[158:159]
	v_pk_fma_f32 v[180:181], v[124:125], v[136:137], v[140:141]
	v_pk_fma_f32 v[182:183], v[126:127], v[138:139], v[142:143]
	v_fmac_f32_dpp v176, v116, v148 row_shr:1 row_mask:0xf bank_mask:0xf bound_ctrl:1
	v_fmac_f32_dpp v177, v117, v149 row_shr:1 row_mask:0xf bank_mask:0xf bound_ctrl:1
	v_fmac_f32_dpp v178, v118, v150 row_shr:1 row_mask:0xf bank_mask:0xf bound_ctrl:1
	v_fmac_f32_dpp v179, v119, v151 row_shr:1 row_mask:0xf bank_mask:0xf bound_ctrl:1
	v_fmac_f32_dpp v176, v116, v144 row_shr:2 row_mask:0xf bank_mask:0xf bound_ctrl:1
	v_fmac_f32_dpp v177, v117, v145 row_shr:2 row_mask:0xf bank_mask:0xf bound_ctrl:1
	v_fmac_f32_dpp v178, v118, v146 row_shr:2 row_mask:0xf bank_mask:0xf bound_ctrl:1
	v_fmac_f32_dpp v179, v119, v147 row_shr:2 row_mask:0xf bank_mask:0xf bound_ctrl:1
	v_fmac_f32_dpp v176, v100, v148 row_shl:15 row_mask:0xf bank_mask:0xf bound_ctrl:1
	v_fmac_f32_dpp v177, v101, v149 row_shl:15 row_mask:0xf bank_mask:0xf bound_ctrl:1
	v_fmac_f32_dpp v178, v102, v150 row_shl:15 row_mask:0xf bank_mask:0xf bound_ctrl:1
	v_fmac_f32_dpp v179, v103, v151 row_shl:15 row_mask:0xf bank_mask:0xf bound_ctrl:1
	v_fmac_f32_dpp v176, v100, v144 row_shl:14 row_mask:0xf bank_mask:0xf bound_ctrl:1
	v_fmac_f32_dpp v177, v101, v145 row_shl:14 row_mask:0xf bank_mask:0xf bound_ctrl:1
	v_fmac_f32_dpp v178, v102, v146 row_shl:14 row_mask:0xf bank_mask:0xf bound_ctrl:1
	v_fmac_f32_dpp v179, v103, v147 row_shl:14 row_mask:0xf bank_mask:0xf bound_ctrl:1
	v_fmac_f32_dpp v180, v124, v132 row_shr:1 row_mask:0xf bank_mask:0xf bound_ctrl:1
	v_fmac_f32_dpp v181, v125, v133 row_shr:1 row_mask:0xf bank_mask:0xf bound_ctrl:1
	v_fmac_f32_dpp v182, v126, v134 row_shr:1 row_mask:0xf bank_mask:0xf bound_ctrl:1
	v_fmac_f32_dpp v183, v127, v135 row_shr:1 row_mask:0xf bank_mask:0xf bound_ctrl:1
	v_fmac_f32_dpp v180, v124, v128 row_shr:2 row_mask:0xf bank_mask:0xf bound_ctrl:1
	v_fmac_f32_dpp v181, v125, v129 row_shr:2 row_mask:0xf bank_mask:0xf bound_ctrl:1
	v_fmac_f32_dpp v182, v126, v130 row_shr:2 row_mask:0xf bank_mask:0xf bound_ctrl:1
	v_fmac_f32_dpp v183, v127, v131 row_shr:2 row_mask:0xf bank_mask:0xf bound_ctrl:1
	v_fmac_f32_dpp v180, v108, v132 row_shl:15 row_mask:0xf bank_mask:0xf bound_ctrl:1
	v_fmac_f32_dpp v181, v109, v133 row_shl:15 row_mask:0xf bank_mask:0xf bound_ctrl:1
	v_fmac_f32_dpp v182, v110, v134 row_shl:15 row_mask:0xf bank_mask:0xf bound_ctrl:1
	v_fmac_f32_dpp v183, v111, v135 row_shl:15 row_mask:0xf bank_mask:0xf bound_ctrl:1
	v_fmac_f32_dpp v180, v108, v128 row_shl:14 row_mask:0xf bank_mask:0xf bound_ctrl:1
	v_fmac_f32_dpp v181, v109, v129 row_shl:14 row_mask:0xf bank_mask:0xf bound_ctrl:1
	v_fmac_f32_dpp v182, v110, v130 row_shl:14 row_mask:0xf bank_mask:0xf bound_ctrl:1
	v_fmac_f32_dpp v183, v111, v131 row_shl:14 row_mask:0xf bank_mask:0xf bound_ctrl:1
	v_pk_mul_f32 v[184:185], v[176:177], v[176:177]
	v_pk_mul_f32 v[186:187], v[178:179], v[178:179]
	v_pk_fma_f32 v[184:185], v[184:185], v[238:239], v[240:241]
	v_pk_fma_f32 v[186:187], v[186:187], v[238:239], v[240:241]
	v_pk_mul_f32 v[184:185], v[176:177], v[184:185]
	v_pk_mul_f32 v[186:187], v[178:179], v[186:187]
	v_exp_f32_e32 v184, v184
	v_exp_f32_e32 v185, v185
	v_exp_f32_e32 v186, v186
	v_exp_f32_e32 v187, v187
	s_nop 0
	v_pk_add_f32 v[184:185], v[184:185], v[242:243]
	v_pk_add_f32 v[186:187], v[186:187], v[242:243]
	v_rcp_f32_e32 v184, v184
	v_rcp_f32_e32 v185, v185
	v_rcp_f32_e32 v186, v186
	v_rcp_f32_e32 v187, v187
	v_mad_i64_i32 v[168:169], s[0:1], v216, s88, v[246:247]
	v_pk_mul_f32 v[184:185], v[176:177], v[184:185]
	v_pk_mul_f32 v[186:187], v[178:179], v[186:187]
	v_pk_mul_f32 v[184:185], v[184:185], v[180:181]
	v_pk_mul_f32 v[186:187], v[186:187], v[182:183]
	v_mov_b32_e32 v188, v217
	v_mov_b32_e32 v189, v219
	v_cvt_pk_bf16_f32 v190, v184, v185
	v_cvt_pk_bf16_f32 v191, v186, v187
	global_store_dwordx4 v[168:169], v[188:191], off
